# H epilogue: second stats-load batch hoisted into free VGPRs (one wait); attention PV: counted lgkmcnt(6/4/2/0) per MFMA instead of lgkmcnt(0) per group
# speedup vs baseline: 1.0279x; 1.0030x over previous
.LBB0_561:
	ds_read_b128 v[64:67], v189 offset:49152
	ds_read_b128 v[68:71], v189 offset:57344
	ds_read_b128 v[210:213], v190 offset:49152
	ds_read_b128 v[218:221], v190 offset:57344
	s_add_i32 s0, 0, 0x12000
	v_add_f32_e32 v148, 0, v175
	s_waitcnt lgkmcnt(3)
	v_mfma_f32_32x32x16_bf16 v[80:95], v[64:67], v[120:123], 0
	v_add_f32_e32 v148, v217, v148
	v_add_f32_e32 v148, v149, v148
	v_add_f32_e32 v148, v216, v148
	v_add_f32_e32 v148, v150, v148
	v_add_f32_e32 v148, v174, v148
	v_add_f32_e32 v148, v151, v148
	v_add_f32_e32 v148, v173, v148
	s_waitcnt lgkmcnt(2)
	v_mfma_f32_32x32x16_bf16 v[64:79], v[68:71], v[120:123], 0
	v_add_f32_e32 v148, v154, v148
	v_add_f32_e32 v148, v172, v148
	v_add_f32_e32 v148, v153, v148
	v_add_f32_e32 v148, v155, v148
	v_exp_f32_e32 v140, v140
	v_add_f32_e32 v148, v145, v148
	v_exp_f32_e32 v141, v141
	s_waitcnt lgkmcnt(1)
	v_mfma_f32_32x32x16_bf16 v[80:95], v[210:213], v[124:127], v[80:95]
	v_add_f32_e32 v148, v147, v148
	v_exp_f32_e32 v138, v138
	v_add_f32_e32 v148, v144, v148
	v_exp_f32_e32 v139, v139
	v_add_f32_e32 v148, v146, v148
	v_exp_f32_e32 v132, v132
	v_add_f32_e32 v148, v140, v148
	s_waitcnt lgkmcnt(0)
	v_mfma_f32_32x32x16_bf16 v[64:79], v[218:221], v[124:127], v[64:79]
	ds_read_b128 v[210:213], v191 offset:49152
	ds_read_b128 v[218:221], v191 offset:57344
	v_exp_f32_e32 v133, v133
	v_add_f32_e32 v148, v141, v148
	v_exp_f32_e32 v130, v130
	v_add_f32_e32 v148, v138, v148
	v_exp_f32_e32 v131, v131
	v_add_f32_e32 v148, v139, v148
	s_waitcnt lgkmcnt(1)
	v_mfma_f32_32x32x16_bf16 v[80:95], v[210:213], v[116:119], v[80:95]
	v_exp_f32_e32 v128, v128
	v_add_f32_e32 v148, v132, v148
	v_exp_f32_e32 v129, v129
	v_add_f32_e32 v148, v133, v148
	v_exp_f32_e32 v142, v142
	v_add_f32_e32 v148, v130, v148
	v_exp_f32_e32 v143, v143
	s_waitcnt lgkmcnt(0)
	v_mfma_f32_32x32x16_bf16 v[64:79], v[218:221], v[116:119], v[64:79]
	ds_read_b128 v[210:213], v192 offset:49152
	ds_read_b128 v[218:221], v192 offset:57344
	v_add_f32_e32 v148, v131, v148
	v_exp_f32_e32 v136, v136
	v_add_f32_e32 v148, v128, v148
	v_exp_f32_e32 v137, v137
	v_add_f32_e32 v148, v129, v148
	v_exp_f32_e32 v134, v134
	s_waitcnt lgkmcnt(1)
	v_mfma_f32_32x32x16_bf16 v[80:95], v[210:213], v[112:115], v[80:95]
	v_add_f32_e32 v148, v142, v148
	v_exp_f32_e32 v135, v135
	v_add_f32_e32 v148, v143, v148
	v_add_f32_e32 v148, v136, v148
	v_add_f32_e32 v148, v137, v148
	v_add_f32_e32 v148, v134, v148
	s_waitcnt lgkmcnt(0)
	v_mfma_f32_32x32x16_bf16 v[64:79], v[218:221], v[112:115], v[64:79]
	ds_read_b128 v[210:213], v193 offset:49152
	ds_read_b128 v[218:221], v193 offset:57344
	ds_read_b128 v[232:235], v194 offset:49152
	ds_read_b128 v[236:239], v194 offset:57344
	s_waitcnt lgkmcnt(3)
	v_mfma_f32_32x32x16_bf16 v[80:95], v[210:213], v[108:111], v[80:95]
	s_waitcnt lgkmcnt(2)
	v_mfma_f32_32x32x16_bf16 v[64:79], v[218:221], v[108:111], v[64:79]
	ds_read_b128 v[210:213], v195 offset:49152
	ds_read_b128 v[218:221], v195 offset:57344
	s_waitcnt lgkmcnt(3)
	v_mfma_f32_32x32x16_bf16 v[80:95], v[232:235], v[104:107], v[80:95]
	s_waitcnt lgkmcnt(2)
	v_mfma_f32_32x32x16_bf16 v[64:79], v[236:239], v[104:107], v[64:79]
	ds_read_b128 v[232:235], v196 offset:49152
	ds_read_b128 v[236:239], v196 offset:57344
	s_waitcnt lgkmcnt(3)
	v_mfma_f32_32x32x16_bf16 v[80:95], v[210:213], v[100:103], v[80:95]
	v_add_u32_e32 v230, s0, v198
	v_add_u32_e32 v231, s0, v200
	s_waitcnt lgkmcnt(2)
	v_mfma_f32_32x32x16_bf16 v[64:79], v[218:221], v[100:103], v[64:79]
	ds_read_b128 v[210:213], v230
	ds_read_b128 v[218:221], v230 offset:4096
	ds_read_b128 v[222:225], v197
	s_waitcnt lgkmcnt(4)
	v_mfma_f32_32x32x16_bf16 v[80:95], v[232:235], v[96:99], v[80:95]
	s_waitcnt lgkmcnt(3)
	v_mfma_f32_32x32x16_bf16 v[64:79], v[236:239], v[96:99], v[64:79]
	ds_read_b128 v[232:235], v231
	ds_read_b128 v[236:239], v231 offset:4096
	ds_read_b128 v[226:229], v184
	s_waitcnt lgkmcnt(3)
	v_mfma_f32_32x32x16_bf16 v[80:95], v[210:213], v[222:225], v[80:95]
	v_mfma_f32_32x32x16_bf16 v[64:79], v[218:221], v[222:225], v[64:79]
	v_add_u32_e32 v244, s0, v202
	v_add_u32_e32 v247, s0, v204
	ds_read_b128 v[210:213], v244
	ds_read_b128 v[218:221], v244 offset:4096
	ds_read_b128 v[222:225], v183
	s_waitcnt lgkmcnt(3)
	v_mfma_f32_32x32x16_bf16 v[80:95], v[232:235], v[226:229], v[80:95]
	v_add_f32_e32 v214, v135, v148
	v_mov_b32_e32 v215, v214
	s_nop 1
	v_permlane32_swap_b32_e32 v214, v215
	v_mfma_f32_32x32x16_bf16 v[64:79], v[236:239], v[226:229], v[64:79]
	ds_read_b128 v[232:235], v247
	ds_read_b128 v[236:239], v247 offset:4096
	ds_read_b128 v[226:229], v182
	s_waitcnt lgkmcnt(3)
	v_mfma_f32_32x32x16_bf16 v[80:95], v[210:213], v[222:225], v[80:95]
	v_mfma_f32_32x32x16_bf16 v[64:79], v[218:221], v[222:225], v[64:79]
	v_cvt_pk_bf16_f32 v148, v175, v217
	v_cvt_pk_bf16_f32 v149, v149, v216
	v_cvt_pk_bf16_f32 v150, v150, v174
	v_cvt_pk_bf16_f32 v151, v151, v173
	v_cvt_pk_bf16_f32 v152, v154, v172
	v_cvt_pk_bf16_f32 v153, v153, v155
	s_waitcnt lgkmcnt(0)
	v_mfma_f32_32x32x16_bf16 v[80:95], v[232:235], v[226:229], v[80:95]
	v_cvt_pk_bf16_f32 v154, v145, v147
	v_permlane32_swap_b32_e32 v148, v150
	v_cvt_pk_bf16_f32 v155, v144, v146
	v_permlane32_swap_b32_e32 v152, v154
	v_cvt_pk_bf16_f32 v216, v140, v141
	v_mfma_f32_32x32x16_bf16 v[64:79], v[236:239], v[226:229], v[64:79]
	v_cvt_pk_bf16_f32 v217, v138, v139
	v_cvt_pk_bf16_f32 v218, v132, v133
	v_cvt_pk_bf16_f32 v219, v130, v131
	v_cvt_pk_bf16_f32 v220, v128, v129
	v_cvt_pk_bf16_f32 v221, v142, v143
	v_cvt_pk_bf16_f32 v222, v136, v137
	v_cvt_pk_bf16_f32 v223, v134, v135
	v_permlane32_swap_b32_e32 v149, v151
	v_permlane32_swap_b32_e32 v153, v155
	v_permlane32_swap_b32_e32 v216, v218
	v_permlane32_swap_b32_e32 v217, v219
	v_permlane32_swap_b32_e32 v220, v222
	v_permlane32_swap_b32_e32 v221, v223
	v_lshl_add_u64 v[172:173], s[64:65], 0, v[158:159]
	s_mov_b32 s0, 0x34e80000
	v_add_co_u32_e32 v132, vcc, s0, v172
	s_mov_b32 s0, 0x34ea0000
	s_nop 0
	v_addc_co_u32_e32 v133, vcc, 0, v173, vcc
	v_add_co_u32_e32 v136, vcc, s0, v172
	v_lshl_add_u64 v[174:175], s[64:65], 0, v[170:171]
	s_nop 0
	v_addc_co_u32_e32 v137, vcc, 0, v173, vcc
	global_load_dwordx4 v[128:131], v[132:133], off offset:256
	s_nop 0
	global_load_dwordx4 v[132:135], v[132:133], off
	s_nop 0
	global_load_dwordx4 v[140:143], v[136:137], off offset:256
	s_nop 0
	global_load_dwordx4 v[136:139], v[136:137], off
	s_mov_b32 s0, 0x1ea04000
	v_add_co_u32_e32 v144, vcc, s0, v174
	s_nop 1
	v_addc_co_u32_e32 v145, vcc, 0, v175, vcc
	global_load_dwordx4 v[144:147], v[144:145], off
	ds_read_b64_tr_b16 v[224:225], v181 offset:0
	ds_read_b64_tr_b16 v[226:227], v181 offset:0x800
	ds_read_b64_tr_b16 v[228:229], v181 offset:0x1000
	ds_read_b64_tr_b16 v[230:231], v181 offset:0x1800
	ds_read_b64_tr_b16 v[232:233], v181 offset:0x2000
	ds_read_b64_tr_b16 v[234:235], v181 offset:0x2800
	ds_read_b64_tr_b16 v[236:237], v181 offset:0x3000
	ds_read_b64_tr_b16 v[238:239], v181 offset:0x3800
	s_nop 0
	s_waitcnt lgkmcnt(6)
	v_mfma_f32_32x32x16_bf16 v[0:15], v[148:151], v[224:227], v[0:15]
	ds_read_b64_tr_b16 v[224:225], v181 offset:0x200
	ds_read_b64_tr_b16 v[226:227], v181 offset:0xa00
	s_waitcnt lgkmcnt(6)
	v_mfma_f32_32x32x16_bf16 v[0:15], v[152:155], v[228:231], v[0:15]
	ds_read_b64_tr_b16 v[228:229], v181 offset:0x1200
	ds_read_b64_tr_b16 v[230:231], v181 offset:0x1a00
	s_waitcnt lgkmcnt(6)
	v_mfma_f32_32x32x16_bf16 v[0:15], v[216:219], v[232:235], v[0:15]
	ds_read_b64_tr_b16 v[232:233], v181 offset:0x2200
	ds_read_b64_tr_b16 v[234:235], v181 offset:0x2a00
	s_waitcnt lgkmcnt(6)
	v_mfma_f32_32x32x16_bf16 v[0:15], v[220:223], v[236:239], v[0:15]
	ds_read_b64_tr_b16 v[236:237], v181 offset:0x3200
	ds_read_b64_tr_b16 v[238:239], v181 offset:0x3a00
	s_waitcnt lgkmcnt(6)
	v_mfma_f32_32x32x16_bf16 v[48:63], v[148:151], v[224:227], v[48:63]
	ds_read_b64_tr_b16 v[224:225], v181 offset:0x400
	ds_read_b64_tr_b16 v[226:227], v181 offset:0xc00
	s_waitcnt lgkmcnt(6)
	v_mfma_f32_32x32x16_bf16 v[48:63], v[152:155], v[228:231], v[48:63]
	ds_read_b64_tr_b16 v[228:229], v181 offset:0x1400
	ds_read_b64_tr_b16 v[230:231], v181 offset:0x1c00
	s_waitcnt lgkmcnt(6)
	v_mfma_f32_32x32x16_bf16 v[48:63], v[216:219], v[232:235], v[48:63]
	ds_read_b64_tr_b16 v[232:233], v181 offset:0x2400
	ds_read_b64_tr_b16 v[234:235], v181 offset:0x2c00
	s_waitcnt lgkmcnt(6)
	v_mfma_f32_32x32x16_bf16 v[48:63], v[220:223], v[236:239], v[48:63]
	ds_read_b64_tr_b16 v[236:237], v181 offset:0x3400
	ds_read_b64_tr_b16 v[238:239], v181 offset:0x3c00
	s_waitcnt lgkmcnt(6)
	v_mfma_f32_32x32x16_bf16 v[32:47], v[148:151], v[224:227], v[32:47]
	ds_read_b64_tr_b16 v[224:225], v181 offset:0x600
	ds_read_b64_tr_b16 v[226:227], v181 offset:0xe00
	s_waitcnt lgkmcnt(6)
	v_mfma_f32_32x32x16_bf16 v[32:47], v[152:155], v[228:231], v[32:47]
	ds_read_b64_tr_b16 v[228:229], v181 offset:0x1600
	ds_read_b64_tr_b16 v[230:231], v181 offset:0x1e00
	s_waitcnt lgkmcnt(6)
	v_mfma_f32_32x32x16_bf16 v[32:47], v[216:219], v[232:235], v[32:47]
	ds_read_b64_tr_b16 v[232:233], v181 offset:0x2600
	ds_read_b64_tr_b16 v[234:235], v181 offset:0x2e00
	s_waitcnt lgkmcnt(6)
	v_mfma_f32_32x32x16_bf16 v[32:47], v[220:223], v[236:239], v[32:47]
	ds_read_b64_tr_b16 v[236:237], v181 offset:0x3600
	ds_read_b64_tr_b16 v[238:239], v181 offset:0x3e00
	s_waitcnt lgkmcnt(6)
	v_mfma_f32_32x32x16_bf16 v[16:31], v[148:151], v[224:227], v[16:31]
	v_max_f32_e32 v148, v81, v81
	v_max_f32_e32 v149, v80, v80
	v_max_f32_e32 v148, v149, v148
	v_max3_f32 v148, v148, v82, v83
	v_max3_f32 v148, v148, v84, v85
	v_max3_f32 v148, v148, v86, v87
	v_max3_f32 v148, v148, v88, v89
	v_max3_f32 v148, v148, v90, v91
	v_max3_f32 v148, v148, v92, v93
	s_waitcnt lgkmcnt(4)
	v_mfma_f32_32x32x16_bf16 v[16:31], v[152:155], v[228:231], v[16:31]
	v_max3_f32 v148, v148, v94, v95
	v_max3_f32 v148, v148, v64, v65
	v_max3_f32 v148, v148, v66, v67
	v_max3_f32 v148, v148, v68, v69
	v_max3_f32 v148, v148, v70, v71
	v_max3_f32 v148, v148, v72, v73
	v_max3_f32 v148, v148, v74, v75
	v_max3_f32 v148, v148, v76, v77
	s_waitcnt lgkmcnt(2)
	v_mfma_f32_32x32x16_bf16 v[16:31], v[216:219], v[232:235], v[16:31]
	v_max3_f32 v148, v148, v78, v79
	v_mov_b32_e32 v149, v148
	s_nop 1
	v_permlane32_swap_b32_e32 v148, v149
	v_max_f32_e32 v149, v149, v149
	v_max_f32_e32 v148, v148, v148
	v_max_f32_e32 v148, v148, v149
	v_sub_f32_e32 v149, v148, v209
	v_cmp_ge_f32_e32 vcc, s90, v149
	v_max_f32_e32 v149, v209, v209
	v_max_f32_e32 v148, v149, v148
	s_waitcnt lgkmcnt(0)
	v_mfma_f32_32x32x16_bf16 v[16:31], v[220:223], v[236:239], v[16:31]
	v_sub_f32_e32 v149, v209, v148
	v_mul_f32_e32 v149, 0x3dd53b94, v149
	v_exp_f32_e32 v149, v149
	s_cmp_eq_u64 vcc, exec
	s_cselect_b64 s[6:7], -1, 0
	s_barrier
	s_waitcnt vmcnt(0)
	v_cndmask_b32_e64 v152, v149, 1.0, s[6:7]
	s_waitcnt vmcnt(4)
	ds_write_b128 v185, v[128:131]
	s_waitcnt vmcnt(2)
	ds_write_b128 v186, v[140:143]
	ds_write_b128 v187, v[132:135] offset:32768
	s_waitcnt vmcnt(1)
	ds_write_b128 v188, v[136:139] offset:32768
	v_add_u32_e32 v128, 0x10000, v207
	v_cmp_gt_f32_e32 vcc, 1.0, v152
	s_waitcnt vmcnt(0)
	ds_write_b128 v128, v[144:147]
	s_cbranch_vccz .LBB0_565
	s_and_saveexec_b64 s[0:1], s[4:5]
	ds_write_b32 v178, v152 offset:128
	s_or_b64 exec, exec, s[0:1]
	s_waitcnt lgkmcnt(0)
	v_add_u32_e32 v140, v157, v160
	ds_read_b128 v[128:131], v140 offset:224
	ds_read_b128 v[132:135], v140 offset:192
	ds_read_b128 v[136:139], v140 offset:160
	ds_read_b128 v[140:143], v140 offset:128
	s_waitcnt lgkmcnt(3)
	v_pk_mul_f32 v[12:13], v[12:13], v[128:129]
	s_waitcnt lgkmcnt(2)
	v_pk_mul_f32 v[8:9], v[8:9], v[132:133]
	s_waitcnt lgkmcnt(1)
	v_pk_mul_f32 v[4:5], v[4:5], v[136:137]
	v_pk_mul_f32 v[14:15], v[14:15], v[130:131]
	v_pk_mul_f32 v[10:11], v[10:11], v[134:135]
	v_pk_mul_f32 v[6:7], v[6:7], v[138:139]
	s_waitcnt lgkmcnt(0)
	v_pk_mul_f32 v[2:3], v[2:3], v[142:143]
	v_pk_mul_f32 v[0:1], v[0:1], v[140:141]
	v_pk_mul_f32 v[60:61], v[60:61], v[128:129]
	v_pk_mul_f32 v[56:57], v[56:57], v[132:133]
	v_pk_mul_f32 v[52:53], v[52:53], v[136:137]
	v_pk_mul_f32 v[62:63], v[62:63], v[130:131]
	v_pk_mul_f32 v[58:59], v[58:59], v[134:135]
	v_pk_mul_f32 v[54:55], v[54:55], v[138:139]
	v_pk_mul_f32 v[50:51], v[50:51], v[142:143]
	v_pk_mul_f32 v[48:49], v[48:49], v[140:141]
	v_pk_mul_f32 v[44:45], v[44:45], v[128:129]
	v_pk_mul_f32 v[40:41], v[40:41], v[132:133]
	v_pk_mul_f32 v[36:37], v[36:37], v[136:137]
	v_pk_mul_f32 v[46:47], v[46:47], v[130:131]
	v_pk_mul_f32 v[42:43], v[42:43], v[134:135]
	v_pk_mul_f32 v[38:39], v[38:39], v[138:139]
	v_pk_mul_f32 v[34:35], v[34:35], v[142:143]
	v_pk_mul_f32 v[32:33], v[32:33], v[140:141]
	v_pk_mul_f32 v[28:29], v[28:29], v[128:129]
	v_pk_mul_f32 v[24:25], v[24:25], v[132:133]
	v_pk_mul_f32 v[20:21], v[20:21], v[136:137]
	v_pk_mul_f32 v[30:31], v[30:31], v[130:131]
	v_pk_mul_f32 v[26:27], v[26:27], v[134:135]
	v_pk_mul_f32 v[22:23], v[22:23], v[138:139]
	v_pk_mul_f32 v[18:19], v[18:19], v[142:143]
	v_pk_mul_f32 v[16:17], v[16:17], v[140:141]
.LBB0_565:
	v_cndmask_b32_e64 v153, v148, v209, s[6:7]
	v_mul_f32_e32 v144, 0xbdd53b94, v153
	v_fmamk_f32 v80, v80, 0x3dd53b94, v144
	v_fmamk_f32 v81, v81, 0x3dd53b94, v144
	v_fmamk_f32 v82, v82, 0x3dd53b94, v144
	v_fmamk_f32 v83, v83, 0x3dd53b94, v144
	v_fmamk_f32 v84, v84, 0x3dd53b94, v144
	v_fmamk_f32 v85, v85, 0x3dd53b94, v144
	v_fmamk_f32 v86, v86, 0x3dd53b94, v144
	v_fmamk_f32 v87, v87, 0x3dd53b94, v144
	v_fmamk_f32 v88, v88, 0x3dd53b94, v144
	v_fmamk_f32 v89, v89, 0x3dd53b94, v144
	v_fmamk_f32 v90, v90, 0x3dd53b94, v144
	v_fmamk_f32 v91, v91, 0x3dd53b94, v144
	v_fmamk_f32 v92, v92, 0x3dd53b94, v144
	v_fmamk_f32 v93, v93, 0x3dd53b94, v144
	v_fmamk_f32 v94, v94, 0x3dd53b94, v144
	v_fmamk_f32 v95, v95, 0x3dd53b94, v144
	v_fmamk_f32 v218, v68, 0x3dd53b94, v144
	v_fmamk_f32 v148, v71, 0x3dd53b94, v144
	v_fmamk_f32 v149, v72, 0x3dd53b94, v144
	v_fmamk_f32 v219, v77, 0x3dd53b94, v144
	v_fmamk_f32 v155, v64, 0x3dd53b94, v144
	v_fmamk_f32 v209, v65, 0x3dd53b94, v144
	v_fmamk_f32 v216, v66, 0x3dd53b94, v144
	v_fmamk_f32 v217, v67, 0x3dd53b94, v144
	v_fmamk_f32 v146, v69, 0x3dd53b94, v144
	v_fmamk_f32 v147, v70, 0x3dd53b94, v144
	v_fmamk_f32 v150, v73, 0x3dd53b94, v144
	v_fmamk_f32 v151, v74, 0x3dd53b94, v144
	v_fmamk_f32 v154, v75, 0x3dd53b94, v144
	v_fmamk_f32 v145, v76, 0x3dd53b94, v144
	v_exp_f32_e32 v141, v80
	v_exp_f32_e32 v143, v81
	v_exp_f32_e32 v139, v82
	v_exp_f32_e32 v142, v83
	v_exp_f32_e32 v138, v84
	v_exp_f32_e32 v140, v85
	v_exp_f32_e32 v136, v86
	v_exp_f32_e32 v137, v87
	v_exp_f32_e32 v133, v88
	v_exp_f32_e32 v135, v89
	v_exp_f32_e32 v132, v90
	v_exp_f32_e32 v134, v91
	v_exp_f32_e32 v129, v92
	v_exp_f32_e32 v131, v93
	v_exp_f32_e32 v128, v94
	v_exp_f32_e32 v130, v95
	v_fmamk_f32 v220, v78, 0x3dd53b94, v144
	v_fmac_f32_e32 v144, 0x3dd53b94, v79
	s_waitcnt lgkmcnt(0)
	s_barrier
	ds_read_b128 v[64:67], v189 offset:32768
	ds_read_b128 v[68:71], v189 offset:40960
	ds_read_b128 v[222:225], v190 offset:32768
	ds_read_b128 v[226:229], v190 offset:40960
	v_exp_f32_e32 v155, v155
	v_exp_f32_e32 v209, v209
	s_waitcnt lgkmcnt(3)
	v_mfma_f32_32x32x16_bf16 v[80:95], v[64:67], v[120:123], 0
	v_exp_f32_e32 v216, v216
	v_exp_f32_e32 v217, v217
	v_exp_f32_e32 v146, v146
	v_exp_f32_e32 v147, v147
	v_exp_f32_e32 v154, v154
	v_exp_f32_e32 v145, v145
	v_exp_f32_e32 v144, v144
	s_waitcnt lgkmcnt(2)
	v_mfma_f32_32x32x16_bf16 v[64:79], v[68:71], v[120:123], 0
	s_waitcnt lgkmcnt(0)
	v_mfma_f32_32x32x16_bf16 v[64:79], v[226:229], v[124:127], v[64:79]
	v_mfma_f32_32x32x16_bf16 v[80:95], v[222:225], v[124:127], v[80:95]
	ds_read_b128 v[222:225], v191 offset:32768
	ds_read_b128 v[226:229], v191 offset:40960
	s_waitcnt lgkmcnt(0)
	v_mfma_f32_32x32x16_bf16 v[64:79], v[226:229], v[116:119], v[64:79]
	v_mfma_f32_32x32x16_bf16 v[80:95], v[222:225], v[116:119], v[80:95]
	ds_read_b128 v[222:225], v192 offset:32768
	ds_read_b128 v[226:229], v192 offset:40960
	s_waitcnt lgkmcnt(0)
	v_mfma_f32_32x32x16_bf16 v[64:79], v[226:229], v[112:115], v[64:79]
	v_mfma_f32_32x32x16_bf16 v[80:95], v[222:225], v[112:115], v[80:95]
	ds_read_b128 v[222:225], v193 offset:32768
	ds_read_b128 v[226:229], v193 offset:40960
	s_waitcnt lgkmcnt(0)
	v_mfma_f32_32x32x16_bf16 v[64:79], v[226:229], v[108:111], v[64:79]
	v_mfma_f32_32x32x16_bf16 v[80:95], v[222:225], v[108:111], v[80:95]
	ds_read_b128 v[222:225], v194 offset:32768
	ds_read_b128 v[226:229], v194 offset:40960
	s_waitcnt lgkmcnt(0)
	v_mfma_f32_32x32x16_bf16 v[64:79], v[226:229], v[104:107], v[64:79]
	v_mfma_f32_32x32x16_bf16 v[80:95], v[222:225], v[104:107], v[80:95]
	ds_read_b128 v[222:225], v195 offset:32768
	ds_read_b128 v[226:229], v195 offset:40960
	s_waitcnt lgkmcnt(0)
	v_mfma_f32_32x32x16_bf16 v[64:79], v[226:229], v[100:103], v[64:79]
	v_mfma_f32_32x32x16_bf16 v[80:95], v[222:225], v[100:103], v[80:95]
	ds_read_b128 v[222:225], v196 offset:32768
	ds_read_b128 v[226:229], v196 offset:40960
	s_waitcnt lgkmcnt(0)
	v_mfma_f32_32x32x16_bf16 v[64:79], v[226:229], v[96:99], v[64:79]
	v_mfma_f32_32x32x16_bf16 v[80:95], v[222:225], v[96:99], v[80:95]
	ds_read_b128 v[222:225], v199
	ds_read_b128 v[226:229], v199 offset:4096
	ds_read_b128 v[230:233], v197
	s_waitcnt lgkmcnt(0)
	v_mfma_f32_32x32x16_bf16 v[64:79], v[226:229], v[230:233], v[64:79]
	v_mfma_f32_32x32x16_bf16 v[80:95], v[222:225], v[230:233], v[80:95]
	ds_read_b128 v[222:225], v201
	ds_read_b128 v[226:229], v201 offset:4096
	ds_read_b128 v[230:233], v184
	s_waitcnt lgkmcnt(0)
	v_mfma_f32_32x32x16_bf16 v[64:79], v[226:229], v[230:233], v[64:79]
	v_mfma_f32_32x32x16_bf16 v[80:95], v[222:225], v[230:233], v[80:95]
	ds_read_b128 v[222:225], v203
	ds_read_b128 v[226:229], v203 offset:4096
	ds_read_b128 v[230:233], v183
	s_waitcnt lgkmcnt(0)
	v_mfma_f32_32x32x16_bf16 v[64:79], v[226:229], v[230:233], v[64:79]
	v_mfma_f32_32x32x16_bf16 v[80:95], v[222:225], v[230:233], v[80:95]
	ds_read_b128 v[222:225], v205
	ds_read_b128 v[226:229], v205 offset:4096
	ds_read_b128 v[230:233], v182
	s_waitcnt lgkmcnt(0)
	v_mfma_f32_32x32x16_bf16 v[64:79], v[226:229], v[230:233], v[64:79]
	v_exp_f32_e32 v227, v148
	v_add_f32_e32 v148, 0, v141
	v_add_f32_e32 v148, v143, v148
	v_add_f32_e32 v148, v139, v148
	v_add_f32_e32 v148, v142, v148
	v_add_f32_e32 v148, v138, v148
	v_add_f32_e32 v148, v140, v148
	v_add_f32_e32 v148, v136, v148
	v_add_f32_e32 v148, v137, v148
	v_add_f32_e32 v148, v133, v148
	v_add_f32_e32 v148, v135, v148
	v_add_f32_e32 v148, v132, v148
	v_add_f32_e32 v148, v134, v148
	v_add_f32_e32 v148, v129, v148
	v_add_f32_e32 v148, v131, v148
	v_add_f32_e32 v148, v128, v148
	v_add_f32_e32 v148, v130, v148
	v_exp_f32_e32 v226, v218
	v_add_f32_e32 v148, v155, v148
	v_add_f32_e32 v148, v209, v148
	v_add_f32_e32 v148, v216, v148
	v_add_f32_e32 v148, v217, v148
	v_exp_f32_e32 v228, v149
	v_add_f32_e32 v148, v226, v148
	v_exp_f32_e32 v229, v150
	v_add_f32_e32 v148, v146, v148
	v_mfma_f32_32x32x16_bf16 v[80:95], v[222:225], v[230:233], v[80:95]
	v_exp_f32_e32 v230, v151
	v_add_f32_e32 v148, v147, v148
	v_add_f32_e32 v148, v227, v148
	v_add_f32_e32 v148, v228, v148
	v_exp_f32_e32 v231, v219
	v_add_f32_e32 v148, v229, v148
	v_exp_f32_e32 v232, v220
	v_add_f32_e32 v148, v230, v148
	v_add_f32_e32 v148, v154, v148
	v_add_f32_e32 v148, v145, v148
	v_add_f32_e32 v148, v231, v148
	v_add_f32_e32 v148, v232, v148
	v_add_f32_e32 v218, v144, v148
	v_mov_b32_e32 v219, v218
	v_cvt_pk_bf16_f32 v148, v141, v143
	v_cvt_pk_bf16_f32 v149, v139, v142
	v_cvt_pk_bf16_f32 v150, v138, v140
	v_cvt_pk_bf16_f32 v151, v136, v137
	s_nop 1
	v_permlane32_swap_b32_e32 v218, v219
	v_permlane32_swap_b32_e32 v148, v150
	v_permlane32_swap_b32_e32 v149, v151
	v_cvt_pk_bf16_f32 v220, v133, v135
	v_cvt_pk_bf16_f32 v221, v132, v134
	v_cvt_pk_bf16_f32 v222, v129, v131
	v_cvt_pk_bf16_f32 v223, v128, v130
	v_cvt_pk_bf16_f32 v224, v155, v209
	v_cvt_pk_bf16_f32 v225, v216, v217
	v_cvt_pk_bf16_f32 v226, v226, v146
	v_cvt_pk_bf16_f32 v227, v147, v227
	v_cvt_pk_bf16_f32 v228, v228, v229
	v_cvt_pk_bf16_f32 v229, v230, v154
	v_cvt_pk_bf16_f32 v230, v145, v231
	v_cvt_pk_bf16_f32 v231, v232, v144
	s_nop 0
	v_permlane32_swap_b32_e32 v220, v222
	v_permlane32_swap_b32_e32 v221, v223
	v_permlane32_swap_b32_e32 v224, v226
	v_permlane32_swap_b32_e32 v225, v227
	v_permlane32_swap_b32_e32 v228, v230
	v_permlane32_swap_b32_e32 v229, v231
	s_mov_b32 s0, 0x34ec0000
	v_add_co_u32_e32 v132, vcc, s0, v172
	s_mov_b32 s0, 0x34ee0000
	s_nop 0
	v_addc_co_u32_e32 v133, vcc, 0, v173, vcc
	v_add_co_u32_e32 v136, vcc, s0, v172
	s_mov_b32 s0, 0x1ea06000
	s_nop 0
	v_addc_co_u32_e32 v137, vcc, 0, v173, vcc
	global_load_dwordx4 v[128:131], v[132:133], off offset:256
	s_nop 0
	global_load_dwordx4 v[132:135], v[132:133], off
	s_nop 0
	global_load_dwordx4 v[140:143], v[136:137], off offset:256
	s_nop 0
	global_load_dwordx4 v[136:139], v[136:137], off
	v_add_co_u32_e32 v144, vcc, s0, v174
	s_nop 1
	v_addc_co_u32_e32 v145, vcc, 0, v175, vcc
	global_load_dwordx4 v[144:147], v[144:145], off
	ds_read_b64_tr_b16 v[172:173], v180 offset:0
	ds_read_b64_tr_b16 v[174:175], v180 offset:0x800
	ds_read_b64_tr_b16 v[232:233], v180 offset:0x1000
	ds_read_b64_tr_b16 v[234:235], v180 offset:0x1800
	ds_read_b64_tr_b16 v[236:237], v180 offset:0x2000
	ds_read_b64_tr_b16 v[238:239], v180 offset:0x2800
	ds_read_b64_tr_b16 v[248:249], v180 offset:0x3000
	ds_read_b64_tr_b16 v[250:251], v180 offset:0x3800
	s_nop 0
	s_waitcnt lgkmcnt(6)
	v_mfma_f32_32x32x16_bf16 v[0:15], v[148:151], v[172:175], v[0:15]
	ds_read_b64_tr_b16 v[172:173], v180 offset:0x200
	ds_read_b64_tr_b16 v[174:175], v180 offset:0xa00
	s_waitcnt lgkmcnt(6)
	v_mfma_f32_32x32x16_bf16 v[0:15], v[220:223], v[232:235], v[0:15]
	ds_read_b64_tr_b16 v[232:233], v180 offset:0x1200
	ds_read_b64_tr_b16 v[234:235], v180 offset:0x1a00
	s_waitcnt lgkmcnt(6)
	v_mfma_f32_32x32x16_bf16 v[0:15], v[224:227], v[236:239], v[0:15]
	ds_read_b64_tr_b16 v[236:237], v180 offset:0x2200
	ds_read_b64_tr_b16 v[238:239], v180 offset:0x2a00
	s_waitcnt lgkmcnt(6)
	v_mfma_f32_32x32x16_bf16 v[0:15], v[228:231], v[248:251], v[0:15]
	ds_read_b64_tr_b16 v[248:249], v180 offset:0x3200
	ds_read_b64_tr_b16 v[250:251], v180 offset:0x3a00
	s_waitcnt lgkmcnt(6)
	v_mfma_f32_32x32x16_bf16 v[48:63], v[148:151], v[172:175], v[48:63]
	ds_read_b64_tr_b16 v[172:173], v180 offset:0x400
	ds_read_b64_tr_b16 v[174:175], v180 offset:0xc00
	s_waitcnt lgkmcnt(6)
	v_mfma_f32_32x32x16_bf16 v[48:63], v[220:223], v[232:235], v[48:63]
	ds_read_b64_tr_b16 v[232:233], v180 offset:0x1400
	ds_read_b64_tr_b16 v[234:235], v180 offset:0x1c00
	s_waitcnt lgkmcnt(6)
	v_mfma_f32_32x32x16_bf16 v[48:63], v[224:227], v[236:239], v[48:63]
	ds_read_b64_tr_b16 v[236:237], v180 offset:0x2400
	ds_read_b64_tr_b16 v[238:239], v180 offset:0x2c00
	s_waitcnt lgkmcnt(6)
	v_mfma_f32_32x32x16_bf16 v[48:63], v[228:231], v[248:251], v[48:63]
	ds_read_b64_tr_b16 v[248:249], v180 offset:0x3400
	ds_read_b64_tr_b16 v[250:251], v180 offset:0x3c00
	s_waitcnt lgkmcnt(6)
	v_mfma_f32_32x32x16_bf16 v[32:47], v[148:151], v[172:175], v[32:47]
	ds_read_b64_tr_b16 v[172:173], v180 offset:0x600
	ds_read_b64_tr_b16 v[174:175], v180 offset:0xe00
	s_waitcnt lgkmcnt(6)
	v_mfma_f32_32x32x16_bf16 v[32:47], v[220:223], v[232:235], v[32:47]
	ds_read_b64_tr_b16 v[232:233], v180 offset:0x1600
	ds_read_b64_tr_b16 v[234:235], v180 offset:0x1e00
	s_waitcnt lgkmcnt(6)
	v_mfma_f32_32x32x16_bf16 v[32:47], v[224:227], v[236:239], v[32:47]
	ds_read_b64_tr_b16 v[236:237], v180 offset:0x2600
	ds_read_b64_tr_b16 v[238:239], v180 offset:0x2e00
	s_waitcnt lgkmcnt(6)
	v_mfma_f32_32x32x16_bf16 v[32:47], v[228:231], v[248:251], v[32:47]
	ds_read_b64_tr_b16 v[248:249], v180 offset:0x3600
	ds_read_b64_tr_b16 v[250:251], v180 offset:0x3e00
	s_waitcnt lgkmcnt(6)
	v_mfma_f32_32x32x16_bf16 v[16:31], v[148:151], v[172:175], v[16:31]
	v_max_f32_e32 v148, v81, v81
	v_max_f32_e32 v149, v80, v80
	v_max_f32_e32 v148, v149, v148
	v_max3_f32 v148, v148, v82, v83
	v_max3_f32 v148, v148, v84, v85
	v_max3_f32 v148, v148, v86, v87
	v_max3_f32 v148, v148, v88, v89
	v_max3_f32 v148, v148, v90, v91
	v_max3_f32 v148, v148, v92, v93
	s_waitcnt lgkmcnt(4)
	v_mfma_f32_32x32x16_bf16 v[16:31], v[220:223], v[232:235], v[16:31]
	v_max3_f32 v148, v148, v94, v95
	v_max3_f32 v148, v148, v64, v65
	v_max3_f32 v148, v148, v66, v67
	v_max3_f32 v148, v148, v68, v69
	v_max3_f32 v148, v148, v70, v71
	v_max3_f32 v148, v148, v72, v73
	v_max3_f32 v148, v148, v74, v75
	v_max3_f32 v148, v148, v76, v77
	s_waitcnt lgkmcnt(2)
	v_mfma_f32_32x32x16_bf16 v[16:31], v[224:227], v[236:239], v[16:31]
	v_max3_f32 v148, v148, v78, v79
	v_mov_b32_e32 v149, v148
	s_nop 1
	v_permlane32_swap_b32_e32 v148, v149
	v_max_f32_e32 v149, v149, v149
	v_max_f32_e32 v148, v148, v148
	v_max_f32_e32 v148, v148, v149
	v_sub_f32_e32 v149, v148, v153
	v_cmp_ge_f32_e32 vcc, s90, v149
	v_max_f32_e32 v149, v153, v153
	v_max_f32_e32 v149, v149, v148
	s_waitcnt lgkmcnt(0)
	v_mfma_f32_32x32x16_bf16 v[16:31], v[228:231], v[248:251], v[16:31]
	v_sub_f32_e32 v148, v153, v149
	v_mul_f32_e32 v148, 0x3dd53b94, v148
	v_exp_f32_e32 v148, v148
	s_cmp_eq_u64 vcc, exec
	s_cselect_b64 s[6:7], -1, 0
	s_barrier
	s_waitcnt vmcnt(0)
	v_cndmask_b32_e64 v148, v148, 1.0, s[6:7]
	v_cmp_gt_f32_e32 vcc, 1.0, v148
	s_waitcnt vmcnt(4)
	ds_write_b128 v185, v[128:131] offset:16384
	s_waitcnt vmcnt(2)
	ds_write_b128 v186, v[140:143] offset:16384
	ds_write_b128 v187, v[132:135] offset:49152
	s_waitcnt vmcnt(1)
	ds_write_b128 v188, v[136:139] offset:49152
	s_waitcnt vmcnt(0)
	ds_write_b128 v208, v[144:147]
	s_cbranch_vccz .LBB0_569
	s_and_saveexec_b64 s[0:1], s[4:5]
	ds_write_b32 v178, v148 offset:128
	s_or_b64 exec, exec, s[0:1]
	s_waitcnt lgkmcnt(0)
	v_add_u32_e32 v140, v157, v160
	ds_read_b128 v[128:131], v140 offset:224
	ds_read_b128 v[132:135], v140 offset:192
	ds_read_b128 v[136:139], v140 offset:160
	ds_read_b128 v[140:143], v140 offset:128
	s_waitcnt lgkmcnt(3)
	v_pk_mul_f32 v[12:13], v[12:13], v[128:129]
	s_waitcnt lgkmcnt(2)
	v_pk_mul_f32 v[8:9], v[8:9], v[132:133]
	s_waitcnt lgkmcnt(1)
	v_pk_mul_f32 v[4:5], v[4:5], v[136:137]
	v_pk_mul_f32 v[14:15], v[14:15], v[130:131]
	v_pk_mul_f32 v[10:11], v[10:11], v[134:135]
	v_pk_mul_f32 v[6:7], v[6:7], v[138:139]
	s_waitcnt lgkmcnt(0)
	v_pk_mul_f32 v[2:3], v[2:3], v[142:143]
	v_pk_mul_f32 v[0:1], v[0:1], v[140:141]
	v_pk_mul_f32 v[60:61], v[60:61], v[128:129]
	v_pk_mul_f32 v[56:57], v[56:57], v[132:133]
	v_pk_mul_f32 v[52:53], v[52:53], v[136:137]
	v_pk_mul_f32 v[62:63], v[62:63], v[130:131]
	v_pk_mul_f32 v[58:59], v[58:59], v[134:135]
	v_pk_mul_f32 v[54:55], v[54:55], v[138:139]
	v_pk_mul_f32 v[50:51], v[50:51], v[142:143]
	v_pk_mul_f32 v[48:49], v[48:49], v[140:141]
	v_pk_mul_f32 v[44:45], v[44:45], v[128:129]
	v_pk_mul_f32 v[40:41], v[40:41], v[132:133]
	v_pk_mul_f32 v[36:37], v[36:37], v[136:137]
	v_pk_mul_f32 v[46:47], v[46:47], v[130:131]
	v_pk_mul_f32 v[42:43], v[42:43], v[134:135]
	v_pk_mul_f32 v[38:39], v[38:39], v[138:139]
	v_pk_mul_f32 v[34:35], v[34:35], v[142:143]
	v_pk_mul_f32 v[32:33], v[32:33], v[140:141]
	v_pk_mul_f32 v[28:29], v[28:29], v[128:129]
	v_pk_mul_f32 v[24:25], v[24:25], v[132:133]
	v_pk_mul_f32 v[20:21], v[20:21], v[136:137]
	v_pk_mul_f32 v[30:31], v[30:31], v[130:131]
	v_pk_mul_f32 v[26:27], v[26:27], v[134:135]
	v_pk_mul_f32 v[22:23], v[22:23], v[138:139]
	v_pk_mul_f32 v[18:19], v[18:19], v[142:143]
	v_pk_mul_f32 v[16:17], v[16:17], v[140:141]

.LBB0_1056:
	s_add_u32 s0, s78, 0xfff80080
	s_addc_u32 s1, s79, -1
	s_add_i32 s50, 0, 0x10000
	v_add_u32_e32 v76, s50, v205
	ds_read_b128 v[64:67], v76
	ds_read_b128 v[68:71], v76 offset:1024
	ds_read_b128 v[72:75], v76 offset:2048
	ds_read_b128 v[76:79], v76 offset:3072
	s_cmp_eq_u32 s47, 28
	s_cselect_b32 s81, s14, s1
	s_cselect_b32 s80, s15, s0
	s_cselect_b32 s1, s16, s13
	s_cselect_b32 s0, s17, s12
	ds_read_b128 v[80:83], v207
	ds_read_b128 v[84:87], v207 offset:1024
	ds_read_b128 v[88:91], v207 offset:2048
	ds_read_b128 v[92:95], v207 offset:3072
	ds_read_b128 v[180:183], v207 offset:4096
	ds_read_b128 v[184:187], v207 offset:5120
	ds_read_b128 v[188:191], v207 offset:6144
	ds_read_b128 v[192:195], v207 offset:7168
	s_waitcnt lgkmcnt(8)
	s_barrier
	s_waitcnt lgkmcnt(0)
	s_waitcnt lgkmcnt(0)
	v_mfma_f32_16x16x32_bf16 v[156:159], v[64:67], v[80:83], v[156:159]
	v_mfma_f32_16x16x32_bf16 v[152:155], v[72:75], v[80:83], v[152:155]
	v_mfma_f32_16x16x32_bf16 v[148:151], v[64:67], v[88:91], v[148:151]
	v_mfma_f32_16x16x32_bf16 v[140:143], v[72:75], v[88:91], v[140:143]
	v_mfma_f32_16x16x32_bf16 v[132:135], v[64:67], v[180:183], v[132:135]
	v_mfma_f32_16x16x32_bf16 v[124:127], v[72:75], v[180:183], v[124:127]
	v_mfma_f32_16x16x32_bf16 v[116:119], v[64:67], v[188:191], v[116:119]
	v_mfma_f32_16x16x32_bf16 v[108:111], v[72:75], v[188:191], v[108:111]
	v_mfma_f32_16x16x32_bf16 v[156:159], v[68:71], v[84:87], v[156:159]
	v_mfma_f32_16x16x32_bf16 v[152:155], v[76:79], v[84:87], v[152:155]
	v_mfma_f32_16x16x32_bf16 v[148:151], v[68:71], v[92:95], v[148:151]
	v_mfma_f32_16x16x32_bf16 v[140:143], v[76:79], v[92:95], v[140:143]
	v_mfma_f32_16x16x32_bf16 v[132:135], v[68:71], v[184:187], v[132:135]
	v_mfma_f32_16x16x32_bf16 v[124:127], v[76:79], v[184:187], v[124:127]
	v_mfma_f32_16x16x32_bf16 v[116:119], v[68:71], v[192:195], v[116:119]
	v_mfma_f32_16x16x32_bf16 v[108:111], v[76:79], v[192:195], v[108:111]
	s_barrier
	v_lshl_add_u64 v[196:197], s[78:79], 0, v[176:177]
	s_add_i32 m0, s22, 0xc000
	s_nop 0
	global_load_lds_dwordx4 v[196:197], off
	v_lshl_add_u64 v[196:197], s[78:79], 0, v[178:179]
	s_add_i32 m0, s22, 0xe000
	s_nop 0
	global_load_lds_dwordx4 v[196:197], off
	s_add_i32 s66, 0, 0x14000
	s_add_i32 s50, s50, s21
	v_add_u32_e32 v212, s66, v205
	v_lshl_add_u64 v[224:225], s[0:1], 0, v[160:161]
	s_mov_b32 m0, s50
	ds_read_b128 v[196:199], v212
	ds_read_b128 v[200:203], v212 offset:1024
	ds_read_b128 v[208:211], v212 offset:2048
	ds_read_b128 v[212:215], v212 offset:3072
	global_load_lds_dwordx4 v[224:225], off
	v_lshl_add_u64 v[226:227], s[0:1], 0, v[170:171]
	s_add_i32 m0, s50, 0x2000
	s_nop 0
	global_load_lds_dwordx4 v[226:227], off
	s_barrier
	s_waitcnt lgkmcnt(0)
	s_waitcnt lgkmcnt(0)
	v_mfma_f32_16x16x32_bf16 v[144:147], v[196:199], v[80:83], v[144:147]
	v_mfma_f32_16x16x32_bf16 v[80:83], v[208:211], v[80:83], v[136:139]
	v_mfma_f32_16x16x32_bf16 v[144:147], v[200:203], v[84:87], v[144:147]
	v_mfma_f32_16x16x32_bf16 v[80:83], v[212:215], v[84:87], v[80:83]
	v_mfma_f32_16x16x32_bf16 v[84:87], v[196:199], v[88:91], v[128:131]
	v_mfma_f32_16x16x32_bf16 v[88:91], v[208:211], v[88:91], v[120:123]
	v_mfma_f32_16x16x32_bf16 v[104:107], v[208:211], v[180:183], v[104:107]
	v_mfma_f32_16x16x32_bf16 v[100:103], v[196:199], v[188:191], v[100:103]
	v_mfma_f32_16x16x32_bf16 v[96:99], v[208:211], v[188:191], v[96:99]
	v_mfma_f32_16x16x32_bf16 v[84:87], v[200:203], v[92:95], v[84:87]
	v_mfma_f32_16x16x32_bf16 v[88:91], v[212:215], v[92:95], v[88:91]
	v_mfma_f32_16x16x32_bf16 v[92:95], v[196:199], v[180:183], v[112:115]
	v_mfma_f32_16x16x32_bf16 v[104:107], v[212:215], v[184:187], v[104:107]
	v_mfma_f32_16x16x32_bf16 v[100:103], v[200:203], v[192:195], v[100:103]
	v_mfma_f32_16x16x32_bf16 v[96:99], v[212:215], v[192:195], v[96:99]
	v_mfma_f32_16x16x32_bf16 v[92:95], v[200:203], v[184:187], v[92:95]
	s_mov_b32 m0, s22
	v_lshl_add_u64 v[228:229], s[80:81], 0, v[174:175]
	s_barrier
	ds_read_b128 v[112:115], v207 offset:16384
	ds_read_b128 v[120:123], v207 offset:17408
	ds_read_b128 v[128:131], v207 offset:18432
	ds_read_b128 v[136:139], v207 offset:19456
	ds_read_b128 v[180:183], v207 offset:20480
	ds_read_b128 v[184:187], v207 offset:21504
	ds_read_b128 v[188:191], v207 offset:22528
	ds_read_b128 v[192:195], v207 offset:23552
	global_load_lds_dwordx4 v[228:229], off
	v_lshl_add_u64 v[230:231], s[80:81], 0, v[172:173]
	s_mov_b32 m0, s23
	s_nop 0
	global_load_lds_dwordx4 v[230:231], off
	s_waitcnt vmcnt(10)
	s_barrier
	s_waitcnt lgkmcnt(0)
	s_waitcnt lgkmcnt(0)
	v_mfma_f32_16x16x32_bf16 v[60:63], v[64:67], v[112:115], v[60:63]
	v_mfma_f32_16x16x32_bf16 v[56:59], v[72:75], v[112:115], v[56:59]
	v_mfma_f32_16x16x32_bf16 v[44:47], v[64:67], v[128:131], v[44:47]
	v_mfma_f32_16x16x32_bf16 v[40:43], v[72:75], v[128:131], v[40:43]
	v_mfma_f32_16x16x32_bf16 v[28:31], v[64:67], v[180:183], v[28:31]
	v_mfma_f32_16x16x32_bf16 v[24:27], v[72:75], v[180:183], v[24:27]
	v_mfma_f32_16x16x32_bf16 v[12:15], v[64:67], v[188:191], v[12:15]
	v_mfma_f32_16x16x32_bf16 v[8:11], v[72:75], v[188:191], v[8:11]
	v_mfma_f32_16x16x32_bf16 v[60:63], v[68:71], v[120:123], v[60:63]
	v_mfma_f32_16x16x32_bf16 v[56:59], v[76:79], v[120:123], v[56:59]
	v_mfma_f32_16x16x32_bf16 v[44:47], v[68:71], v[136:139], v[44:47]
	v_mfma_f32_16x16x32_bf16 v[40:43], v[76:79], v[136:139], v[40:43]
	v_mfma_f32_16x16x32_bf16 v[28:31], v[68:71], v[184:187], v[28:31]
	v_mfma_f32_16x16x32_bf16 v[24:27], v[76:79], v[184:187], v[24:27]
	v_mfma_f32_16x16x32_bf16 v[12:15], v[68:71], v[192:195], v[12:15]
	v_mfma_f32_16x16x32_bf16 v[8:11], v[76:79], v[192:195], v[8:11]
	s_barrier
	s_add_u32 s50, s0, 0x80000
	s_addc_u32 s51, s1, 0
	s_add_i32 s66, s66, s21
	v_lshl_add_u64 v[64:65], s[50:51], 0, v[160:161]
	s_mov_b32 m0, s66
	s_nop 0
	global_load_lds_dwordx4 v[64:65], off
	v_lshl_add_u64 v[64:65], s[50:51], 0, v[170:171]
	s_add_i32 m0, s66, 0x2000
	s_nop 0
	global_load_lds_dwordx4 v[64:65], off
	v_add_u32_e32 v76, 0x18000, v205
	ds_read_b128 v[64:67], v76
	ds_read_b128 v[68:71], v76 offset:1024
	ds_read_b128 v[72:75], v76 offset:2048
	ds_read_b128 v[76:79], v76 offset:3072
	s_waitcnt vmcnt(6)
	s_barrier
	v_mfma_f32_16x16x32_bf16 v[52:55], v[196:199], v[112:115], v[52:55]
	v_mfma_f32_16x16x32_bf16 v[48:51], v[208:211], v[112:115], v[48:51]
	v_mfma_f32_16x16x32_bf16 v[36:39], v[196:199], v[128:131], v[36:39]
	v_mfma_f32_16x16x32_bf16 v[32:35], v[208:211], v[128:131], v[32:35]
	v_mfma_f32_16x16x32_bf16 v[20:23], v[196:199], v[180:183], v[20:23]
	v_mfma_f32_16x16x32_bf16 v[16:19], v[208:211], v[180:183], v[16:19]
	v_mfma_f32_16x16x32_bf16 v[4:7], v[196:199], v[188:191], v[4:7]
	v_mfma_f32_16x16x32_bf16 v[0:3], v[208:211], v[188:191], v[0:3]
	v_mfma_f32_16x16x32_bf16 v[52:55], v[200:203], v[120:123], v[52:55]
	v_mfma_f32_16x16x32_bf16 v[48:51], v[212:215], v[120:123], v[48:51]
	v_mfma_f32_16x16x32_bf16 v[36:39], v[200:203], v[136:139], v[36:39]
	v_mfma_f32_16x16x32_bf16 v[32:35], v[212:215], v[136:139], v[32:35]
	v_mfma_f32_16x16x32_bf16 v[20:23], v[200:203], v[184:187], v[20:23]
	v_mfma_f32_16x16x32_bf16 v[16:19], v[212:215], v[184:187], v[16:19]
	v_mfma_f32_16x16x32_bf16 v[4:7], v[200:203], v[192:195], v[4:7]
	v_mfma_f32_16x16x32_bf16 v[0:3], v[212:215], v[192:195], v[0:3]
	s_add_i32 s66, 0, 0x18000
	s_barrier
	ds_read_b128 v[112:115], v207 offset:32768
	ds_read_b128 v[120:123], v207 offset:33792
	ds_read_b128 v[180:183], v207 offset:34816
	ds_read_b128 v[184:187], v207 offset:35840
	ds_read_b128 v[188:191], v207 offset:36864
	ds_read_b128 v[192:195], v207 offset:37888
	ds_read_b128 v[196:199], v207 offset:38912
	ds_read_b128 v[200:203], v207 offset:39936
	s_waitcnt lgkmcnt(8)
	s_barrier
	s_waitcnt lgkmcnt(0)
	s_waitcnt lgkmcnt(0)
	v_mfma_f32_16x16x32_bf16 v[128:131], v[64:67], v[112:115], v[156:159]
	v_mfma_f32_16x16x32_bf16 v[156:159], v[68:71], v[120:123], v[128:131]
	v_mfma_f32_16x16x32_bf16 v[128:131], v[72:75], v[112:115], v[152:155]
	v_mfma_f32_16x16x32_bf16 v[152:155], v[76:79], v[120:123], v[128:131]
	v_mfma_f32_16x16x32_bf16 v[128:131], v[64:67], v[180:183], v[148:151]
	v_mfma_f32_16x16x32_bf16 v[148:151], v[68:71], v[184:187], v[128:131]
	v_mfma_f32_16x16x32_bf16 v[128:131], v[72:75], v[180:183], v[140:143]
	v_mfma_f32_16x16x32_bf16 v[140:143], v[76:79], v[184:187], v[128:131]
	v_mfma_f32_16x16x32_bf16 v[128:131], v[64:67], v[188:191], v[132:135]
	v_mfma_f32_16x16x32_bf16 v[124:127], v[72:75], v[188:191], v[124:127]
	v_mfma_f32_16x16x32_bf16 v[116:119], v[64:67], v[196:199], v[116:119]
	v_mfma_f32_16x16x32_bf16 v[108:111], v[72:75], v[196:199], v[108:111]
	v_mfma_f32_16x16x32_bf16 v[132:135], v[68:71], v[192:195], v[128:131]
	v_mfma_f32_16x16x32_bf16 v[124:127], v[76:79], v[192:195], v[124:127]
	v_mfma_f32_16x16x32_bf16 v[116:119], v[68:71], v[200:203], v[116:119]
	v_mfma_f32_16x16x32_bf16 v[108:111], v[76:79], v[200:203], v[108:111]
	s_barrier
	s_add_u32 s50, s80, 0x80000
	s_addc_u32 s51, s81, 0
	v_lshl_add_u64 v[128:129], s[50:51], 0, v[174:175]
	s_mov_b32 m0, s24
	s_nop 0
	global_load_lds_dwordx4 v[128:129], off
	v_lshl_add_u64 v[128:129], s[50:51], 0, v[172:173]
	s_mov_b32 m0, s25
	s_nop 0
	global_load_lds_dwordx4 v[128:129], off
	s_add_i32 s50, 0, 0x1c000
	v_add_u32_e32 v128, s50, v205
	s_add_i32 s51, s66, s21
	ds_read_b128 v[208:211], v128
	ds_read_b128 v[212:215], v128 offset:1024
	ds_read_b128 v[216:219], v128 offset:2048
	ds_read_b128 v[220:223], v128 offset:3072
	v_lshl_add_u64 v[128:129], v[224:225], 0, s[92:93]
	s_mov_b32 m0, s51
	s_nop 0
	global_load_lds_dwordx4 v[128:129], off
	v_lshl_add_u64 v[128:129], v[226:227], 0, s[92:93]
	s_add_i32 m0, s51, 0x2000
	s_nop 0
	global_load_lds_dwordx4 v[128:129], off
	s_barrier
	s_waitcnt lgkmcnt(0)
	s_waitcnt lgkmcnt(0)
	v_mfma_f32_16x16x32_bf16 v[80:83], v[216:219], v[112:115], v[80:83]
	v_mfma_f32_16x16x32_bf16 v[128:131], v[208:211], v[112:115], v[144:147]
	v_mfma_f32_16x16x32_bf16 v[136:139], v[220:223], v[120:123], v[80:83]
	v_mfma_f32_16x16x32_bf16 v[80:83], v[208:211], v[180:183], v[84:87]
	v_mfma_f32_16x16x32_bf16 v[144:147], v[212:215], v[120:123], v[128:131]
	v_mfma_f32_16x16x32_bf16 v[128:131], v[212:215], v[184:187], v[80:83]
	v_mfma_f32_16x16x32_bf16 v[80:83], v[216:219], v[180:183], v[88:91]
	v_mfma_f32_16x16x32_bf16 v[120:123], v[220:223], v[184:187], v[80:83]
	v_mfma_f32_16x16x32_bf16 v[80:83], v[208:211], v[188:191], v[92:95]
	v_mfma_f32_16x16x32_bf16 v[112:115], v[212:215], v[192:195], v[80:83]
	v_mfma_f32_16x16x32_bf16 v[80:83], v[216:219], v[188:191], v[104:107]
	v_mfma_f32_16x16x32_bf16 v[104:107], v[220:223], v[192:195], v[80:83]
	v_mfma_f32_16x16x32_bf16 v[80:83], v[208:211], v[196:199], v[100:103]
	v_mfma_f32_16x16x32_bf16 v[100:103], v[212:215], v[200:203], v[80:83]
	v_mfma_f32_16x16x32_bf16 v[80:83], v[216:219], v[196:199], v[96:99]
	v_mfma_f32_16x16x32_bf16 v[96:99], v[220:223], v[200:203], v[80:83]
	s_mov_b32 m0, s26
	v_lshl_add_u64 v[196:197], v[228:229], 0, s[92:93]
	s_barrier
	s_nop 2
	ds_read_b128 v[80:83], v207 offset:49152
	ds_read_b128 v[84:87], v207 offset:50176
	ds_read_b128 v[88:91], v207 offset:51200
	ds_read_b128 v[92:95], v207 offset:52224
	ds_read_b128 v[180:183], v207 offset:53248
	ds_read_b128 v[184:187], v207 offset:54272
	ds_read_b128 v[188:191], v207 offset:55296
	ds_read_b128 v[192:195], v207 offset:56320
	global_load_lds_dwordx4 v[196:197], off
	v_lshl_add_u64 v[196:197], v[230:231], 0, s[92:93]
	s_mov_b32 m0, s27
	s_nop 0
	global_load_lds_dwordx4 v[196:197], off
	s_barrier
	s_waitcnt lgkmcnt(0)
	s_waitcnt lgkmcnt(0)
	v_mfma_f32_16x16x32_bf16 v[60:63], v[64:67], v[80:83], v[60:63]
	v_mfma_f32_16x16x32_bf16 v[56:59], v[72:75], v[80:83], v[56:59]
	v_mfma_f32_16x16x32_bf16 v[44:47], v[64:67], v[88:91], v[44:47]
	v_mfma_f32_16x16x32_bf16 v[40:43], v[72:75], v[88:91], v[40:43]
	v_mfma_f32_16x16x32_bf16 v[28:31], v[64:67], v[180:183], v[28:31]
	v_mfma_f32_16x16x32_bf16 v[24:27], v[72:75], v[180:183], v[24:27]
	v_mfma_f32_16x16x32_bf16 v[12:15], v[64:67], v[188:191], v[12:15]
	v_mfma_f32_16x16x32_bf16 v[8:11], v[72:75], v[188:191], v[8:11]
	v_mfma_f32_16x16x32_bf16 v[60:63], v[68:71], v[84:87], v[60:63]
	v_mfma_f32_16x16x32_bf16 v[56:59], v[76:79], v[84:87], v[56:59]
	v_mfma_f32_16x16x32_bf16 v[44:47], v[68:71], v[92:95], v[44:47]
	v_mfma_f32_16x16x32_bf16 v[40:43], v[76:79], v[92:95], v[40:43]
	v_mfma_f32_16x16x32_bf16 v[28:31], v[68:71], v[184:187], v[28:31]
	v_mfma_f32_16x16x32_bf16 v[24:27], v[76:79], v[184:187], v[24:27]
	v_mfma_f32_16x16x32_bf16 v[12:15], v[68:71], v[192:195], v[12:15]
	v_mfma_f32_16x16x32_bf16 v[8:11], v[76:79], v[192:195], v[8:11]
	s_barrier
	s_add_u32 s0, s0, 0x80080
	s_addc_u32 s1, s1, 0
	s_add_i32 s50, s50, s21
	v_lshl_add_u64 v[64:65], s[0:1], 0, v[160:161]
	s_mov_b32 m0, s50
	s_nop 0
	global_load_lds_dwordx4 v[64:65], off
	v_lshl_add_u64 v[64:65], s[0:1], 0, v[170:171]
	s_add_i32 m0, s50, 0x2000
	s_nop 0
	global_load_lds_dwordx4 v[64:65], off
	s_waitcnt vmcnt(6)
	s_barrier
	v_mfma_f32_16x16x32_bf16 v[52:55], v[208:211], v[80:83], v[52:55]
	v_mfma_f32_16x16x32_bf16 v[48:51], v[216:219], v[80:83], v[48:51]
	v_mfma_f32_16x16x32_bf16 v[36:39], v[208:211], v[88:91], v[36:39]
	v_mfma_f32_16x16x32_bf16 v[32:35], v[216:219], v[88:91], v[32:35]
	v_mfma_f32_16x16x32_bf16 v[20:23], v[208:211], v[180:183], v[20:23]
	v_mfma_f32_16x16x32_bf16 v[16:19], v[216:219], v[180:183], v[16:19]
	v_mfma_f32_16x16x32_bf16 v[4:7], v[208:211], v[188:191], v[4:7]
	v_mfma_f32_16x16x32_bf16 v[0:3], v[216:219], v[188:191], v[0:3]
	v_mfma_f32_16x16x32_bf16 v[52:55], v[212:215], v[84:87], v[52:55]
	v_mfma_f32_16x16x32_bf16 v[48:51], v[220:223], v[84:87], v[48:51]
	v_mfma_f32_16x16x32_bf16 v[36:39], v[212:215], v[92:95], v[36:39]
	v_mfma_f32_16x16x32_bf16 v[32:35], v[220:223], v[92:95], v[32:35]
	v_mfma_f32_16x16x32_bf16 v[20:23], v[212:215], v[184:187], v[20:23]
	v_mfma_f32_16x16x32_bf16 v[16:19], v[220:223], v[184:187], v[16:19]
	v_mfma_f32_16x16x32_bf16 v[4:7], v[212:215], v[192:195], v[4:7]
	v_mfma_f32_16x16x32_bf16 v[0:3], v[220:223], v[192:195], v[0:3]
	s_add_i32 s47, s47, 2
	s_add_u32 s78, s78, 0x100
	s_addc_u32 s79, s79, 0
	s_add_u32 s12, s12, 0x100
	s_addc_u32 s13, s13, 0
	s_cmp_gt_u32 s47, 29
	s_barrier
	s_cbranch_scc0 .LBB0_1056
	v_lshl_or_b32 v182, s48, 8, v206
	v_ashrrev_i32_e32 v183, 31, v182
	v_lshlrev_b64 v[64:65], 2, v[182:183]
	v_lshl_add_u64 v[66:67], s[44:45], 0, v[64:65]
	v_lshl_add_u64 v[64:65], s[42:43], 0, v[64:65]
	global_load_dwordx4 v[72:75], v[66:67], off offset:16
	global_load_dwordx4 v[92:95], v[66:67], off
	global_load_dwordx4 v[68:71], v[64:65], off offset:16
	global_load_dwordx4 v[88:91], v[64:65], off
	v_or_b32_e32 v64, 0x80, v182
	v_lshl_add_u32 v180, s49, 8, v204
	v_ashrrev_i32_e32 v65, 31, v64
	v_or_b32_e32 v84, 0x84, v182
	v_lshlrev_b64 v[64:65], 2, v[64:65]
	v_ashrrev_i32_e32 v85, 31, v84
	v_ashrrev_i32_e32 v181, 31, v180
	v_lshl_add_u64 v[66:67], s[44:45], 0, v[64:65]
	v_lshl_add_u64 v[76:77], s[42:43], 0, v[64:65]
	v_lshl_add_u64 v[84:85], v[84:85], 2, s[44:45]
	v_lshl_add_u64 v[202:203], v[180:181], 3, s[8:9]
	global_load_dwordx4 v[80:83], v[66:67], off
	s_nop 0
	global_load_dwordx4 v[64:67], v[76:77], off offset:16
	s_nop 0
	global_load_dwordx4 v[76:79], v[76:77], off
	v_add_co_u32_e32 v200, vcc, s89, v202
	global_load_dwordx4 v[84:87], v[84:85], off
	s_nop 0
	v_addc_co_u32_e32 v201, vcc, 0, v203, vcc
	global_load_dwordx2 v[184:185], v[202:203], off
	global_load_dwordx2 v[186:187], v[200:201], off
	global_load_dwordx2 v[208:209], v[202:203], off offset:128
	global_load_dwordx2 v[210:211], v[200:201], off offset:128
	global_load_dwordx2 v[212:213], v[202:203], off offset:256
	global_load_dwordx2 v[214:215], v[200:201], off offset:256
	global_load_dwordx2 v[216:217], v[202:203], off offset:384
	global_load_dwordx2 v[218:219], v[200:201], off offset:384
	global_load_dwordx2 v[232:233], v[202:203], off offset:1024
	global_load_dwordx2 v[234:235], v[200:201], off offset:1024
	global_load_dwordx2 v[236:237], v[202:203], off offset:1152
	global_load_dwordx2 v[238:239], v[200:201], off offset:1152
	global_load_dwordx2 v[240:241], v[202:203], off offset:1280
	global_load_dwordx2 v[242:243], v[200:201], off offset:1280
	global_load_dwordx2 v[248:249], v[202:203], off offset:1408
	global_load_dwordx2 v[250:251], v[200:201], off offset:1408
	s_mov_b64 s[0:1], 0x200000
	v_readlane_b32 s66, v255, 7
	s_mov_b32 s48, s72
	s_mov_b32 s49, s46
	s_mov_b64 s[12:13], s[74:75]
	v_readlane_b32 s67, v255, 8
	s_waitcnt vmcnt(0)
	v_xor_b32_e32 v197, 0x80000000, v75
	v_xor_b32_e32 v196, 0x80000000, v74
	v_xor_b32_e32 v199, 0x80000000, v95
	v_xor_b32_e32 v198, 0x80000000, v94
	v_xor_b32_e32 v195, 0x80000000, v83
	v_xor_b32_e32 v194, 0x80000000, v82
	v_cvt_f32_u32_e32 v188, v186
	v_xor_b32_e32 v193, 0x80000000, v87
	v_xor_b32_e32 v192, 0x80000000, v86
	v_cvt_f32_u32_e32 v189, v184
	v_cvt_f32_i32_e32 v184, v187
	v_cvt_f32_i32_e32 v185, v185
	v_pk_fma_f32 v[184:185], v[188:189], s[88:89], v[184:185] op_sel_hi:[1,0,1]
	s_nop 0
	v_pk_mul_f32 v[220:221], v[184:185], s[94:95] op_sel_hi:[1,0]
	s_nop 0
	v_fma_f32 v184, -v221, v221, v220
	v_add_f32_e32 v184, 0x3727c5ac, v184
	v_rsq_f32_e32 v222, v184
	v_pk_fma_f32 v[74:75], v[196:197], v[220:221], v[154:155] op_sel:[0,1,0]
	v_pk_fma_f32 v[156:157], v[92:93], v[220:221], v[156:157] op_sel:[0,1,0] neg_lo:[1,0,0] neg_hi:[1,0,0]
	v_pk_fma_f32 v[94:95], v[198:199], v[220:221], v[158:159] op_sel:[0,1,0]
	v_pk_fma_f32 v[186:187], v[74:75], v[222:223], v[70:71] op_sel_hi:[1,0,1]
	v_pk_fma_f32 v[74:75], v[80:81], v[220:221], v[144:145] op_sel:[0,1,0] neg_lo:[1,0,0] neg_hi:[1,0,0]
	v_pk_fma_f32 v[82:83], v[194:195], v[220:221], v[146:147] op_sel:[0,1,0]
	v_pk_fma_f32 v[184:185], v[94:95], v[222:223], v[90:91] op_sel_hi:[1,0,1]
	v_pk_fma_f32 v[188:189], v[156:157], v[222:223], v[88:89] op_sel_hi:[1,0,1]
	v_pk_fma_f32 v[94:95], v[72:73], v[220:221], v[152:153] op_sel:[0,1,0] neg_lo:[1,0,0] neg_hi:[1,0,0]
	v_pk_fma_f32 v[152:153], v[82:83], v[222:223], v[78:79] op_sel_hi:[1,0,1]
	v_pk_fma_f32 v[156:157], v[74:75], v[222:223], v[76:77] op_sel_hi:[1,0,1]
	v_pk_fma_f32 v[74:75], v[84:85], v[220:221], v[136:137] op_sel:[0,1,0] neg_lo:[1,0,0] neg_hi:[1,0,0]
	v_pk_fma_f32 v[82:83], v[192:193], v[220:221], v[138:139] op_sel:[0,1,0]
	v_pk_fma_f32 v[158:159], v[74:75], v[222:223], v[64:65] op_sel_hi:[1,0,1]
	v_pk_fma_f32 v[154:155], v[82:83], v[222:223], v[66:67] op_sel_hi:[1,0,1]
	v_cvt_f32_u32_e32 v74, v210
	v_cvt_f32_u32_e32 v75, v208
	v_cvt_f32_i32_e32 v82, v211
	v_cvt_f32_i32_e32 v83, v209
	v_pk_fma_f32 v[190:191], v[94:95], v[222:223], v[68:69] op_sel_hi:[1,0,1]
	v_pk_fma_f32 v[74:75], v[74:75], s[88:89], v[82:83] op_sel_hi:[1,0,1]
	s_nop 0
	v_pk_mul_f32 v[74:75], v[74:75], s[94:95] op_sel_hi:[1,0]
	s_nop 0
	v_fma_f32 v82, -v75, v75, v74
	v_add_f32_e32 v82, 0x3727c5ac, v82
	v_rsq_f32_e32 v82, v82
	v_pk_fma_f32 v[86:87], v[92:93], v[74:75], v[148:149] op_sel:[0,1,0] neg_lo:[1,0,0] neg_hi:[1,0,0]
	v_pk_fma_f32 v[94:95], v[198:199], v[74:75], v[150:151] op_sel:[0,1,0]
	v_pk_fma_f32 v[148:149], v[86:87], v[82:83], v[88:89] op_sel_hi:[1,0,1]
	v_pk_fma_f32 v[86:87], v[72:73], v[74:75], v[140:141] op_sel:[0,1,0] neg_lo:[1,0,0] neg_hi:[1,0,0]
	v_pk_fma_f32 v[144:145], v[94:95], v[82:83], v[90:91] op_sel_hi:[1,0,1]
	v_pk_fma_f32 v[94:95], v[196:197], v[74:75], v[142:143] op_sel:[0,1,0]
	v_pk_fma_f32 v[150:151], v[86:87], v[82:83], v[68:69] op_sel_hi:[1,0,1]
	v_pk_fma_f32 v[86:87], v[80:81], v[74:75], v[128:129] op_sel:[0,1,0] neg_lo:[1,0,0] neg_hi:[1,0,0]
	v_pk_fma_f32 v[146:147], v[94:95], v[82:83], v[70:71] op_sel_hi:[1,0,1]
	v_pk_fma_f32 v[94:95], v[194:195], v[74:75], v[130:131] op_sel:[0,1,0]
	v_pk_fma_f32 v[140:141], v[86:87], v[82:83], v[76:77] op_sel_hi:[1,0,1]
	v_pk_fma_f32 v[86:87], v[84:85], v[74:75], v[120:121] op_sel:[0,1,0] neg_lo:[1,0,0] neg_hi:[1,0,0]
	v_pk_fma_f32 v[74:75], v[192:193], v[74:75], v[122:123] op_sel:[0,1,0]
	v_pk_fma_f32 v[136:137], v[94:95], v[82:83], v[78:79] op_sel_hi:[1,0,1]
	v_pk_fma_f32 v[138:139], v[74:75], v[82:83], v[66:67] op_sel_hi:[1,0,1]
	v_pk_fma_f32 v[142:143], v[86:87], v[82:83], v[64:65] op_sel_hi:[1,0,1]
	v_cvt_f32_u32_e32 v74, v214
	v_cvt_f32_u32_e32 v75, v212
	v_cvt_f32_i32_e32 v82, v215
	v_cvt_f32_i32_e32 v83, v213
	v_pk_fma_f32 v[74:75], v[74:75], s[88:89], v[82:83] op_sel_hi:[1,0,1]
	s_nop 0
	v_pk_mul_f32 v[74:75], v[74:75], s[94:95] op_sel_hi:[1,0]
	s_nop 0
	v_fma_f32 v82, -v75, v75, v74
	v_add_f32_e32 v82, 0x3727c5ac, v82
	v_rsq_f32_e32 v82, v82
	v_pk_fma_f32 v[86:87], v[92:93], v[74:75], v[132:133] op_sel:[0,1,0] neg_lo:[1,0,0] neg_hi:[1,0,0]
	v_pk_fma_f32 v[94:95], v[198:199], v[74:75], v[134:135] op_sel:[0,1,0]
	v_pk_fma_f32 v[130:131], v[86:87], v[82:83], v[88:89] op_sel_hi:[1,0,1]
	v_pk_fma_f32 v[86:87], v[72:73], v[74:75], v[124:125] op_sel:[0,1,0] neg_lo:[1,0,0] neg_hi:[1,0,0]
	v_pk_fma_f32 v[128:129], v[94:95], v[82:83], v[90:91] op_sel_hi:[1,0,1]
	v_pk_fma_f32 v[94:95], v[196:197], v[74:75], v[126:127] op_sel:[0,1,0]
	v_pk_fma_f32 v[132:133], v[86:87], v[82:83], v[68:69] op_sel_hi:[1,0,1]
	v_pk_fma_f32 v[86:87], v[80:81], v[74:75], v[112:113] op_sel:[0,1,0] neg_lo:[1,0,0] neg_hi:[1,0,0]
	v_pk_fma_f32 v[126:127], v[94:95], v[82:83], v[70:71] op_sel_hi:[1,0,1]
	v_pk_fma_f32 v[94:95], v[194:195], v[74:75], v[114:115] op_sel:[0,1,0]
	v_pk_fma_f32 v[122:123], v[86:87], v[82:83], v[76:77] op_sel_hi:[1,0,1]
	v_pk_fma_f32 v[86:87], v[84:85], v[74:75], v[104:105] op_sel:[0,1,0] neg_lo:[1,0,0] neg_hi:[1,0,0]
	v_pk_fma_f32 v[74:75], v[192:193], v[74:75], v[106:107] op_sel:[0,1,0]
	v_pk_fma_f32 v[114:115], v[94:95], v[82:83], v[78:79] op_sel_hi:[1,0,1]
	v_pk_fma_f32 v[120:121], v[74:75], v[82:83], v[66:67] op_sel_hi:[1,0,1]
	v_pk_fma_f32 v[124:125], v[86:87], v[82:83], v[64:65] op_sel_hi:[1,0,1]
	v_cvt_f32_u32_e32 v74, v218
	v_cvt_f32_u32_e32 v75, v216
	v_cvt_f32_i32_e32 v82, v219
	v_cvt_f32_i32_e32 v83, v217
	v_pk_fma_f32 v[74:75], v[74:75], s[88:89], v[82:83] op_sel_hi:[1,0,1]
	s_nop 0
	v_pk_mul_f32 v[82:83], v[74:75], s[94:95] op_sel_hi:[1,0]
	s_nop 0
	v_fma_f32 v74, -v83, v83, v82
	v_add_f32_e32 v74, 0x3727c5ac, v74
	v_rsq_f32_e32 v94, v74
	v_pk_fma_f32 v[74:75], v[92:93], v[82:83], v[116:117] op_sel:[0,1,0] neg_lo:[1,0,0] neg_hi:[1,0,0]
	v_pk_fma_f32 v[86:87], v[198:199], v[82:83], v[118:119] op_sel:[0,1,0]
	v_pk_fma_f32 v[96:97], v[84:85], v[82:83], v[96:97] op_sel:[0,1,0] neg_lo:[1,0,0] neg_hi:[1,0,0]
	v_pk_fma_f32 v[104:105], v[86:87], v[94:95], v[90:91] op_sel_hi:[1,0,1]
	v_pk_fma_f32 v[112:113], v[74:75], v[94:95], v[88:89] op_sel_hi:[1,0,1]
	v_pk_fma_f32 v[74:75], v[72:73], v[82:83], v[108:109] op_sel:[0,1,0] neg_lo:[1,0,0] neg_hi:[1,0,0]
	v_pk_fma_f32 v[86:87], v[196:197], v[82:83], v[110:111] op_sel:[0,1,0]
	v_pk_fma_f32 v[108:109], v[74:75], v[94:95], v[68:69] op_sel_hi:[1,0,1]
	v_pk_fma_f32 v[106:107], v[86:87], v[94:95], v[70:71] op_sel_hi:[1,0,1]
	v_pk_fma_f32 v[86:87], v[80:81], v[82:83], v[100:101] op_sel:[0,1,0] neg_lo:[1,0,0] neg_hi:[1,0,0]
	v_pk_fma_f32 v[74:75], v[194:195], v[82:83], v[102:103] op_sel:[0,1,0]
	v_pk_fma_f32 v[82:83], v[192:193], v[82:83], v[98:99] op_sel:[0,1,0]
	v_pk_fma_f32 v[74:75], v[74:75], v[94:95], v[78:79] op_sel_hi:[1,0,1]
	v_pk_fma_f32 v[86:87], v[86:87], v[94:95], v[76:77] op_sel_hi:[1,0,1]
	v_pk_fma_f32 v[82:83], v[82:83], v[94:95], v[66:67] op_sel_hi:[1,0,1]
	v_pk_fma_f32 v[94:95], v[96:97], v[94:95], v[64:65] op_sel_hi:[1,0,1]
	v_cvt_f32_u32_e32 v201, v232
	v_cvt_f32_u32_e32 v200, v234
	v_cvt_f32_i32_e32 v102, v235
	v_cvt_f32_i32_e32 v103, v233
	v_cvt_f32_i32_e32 v99, v237
	v_cvt_f32_i32_e32 v97, v241
	v_pk_fma_f32 v[102:103], v[200:201], s[88:89], v[102:103] op_sel_hi:[1,0,1]
	s_nop 0
	v_pk_mul_f32 v[102:103], v[102:103], s[94:95] op_sel_hi:[1,0]
	s_nop 0
	v_fma_f32 v110, -v103, v103, v102
	v_add_f32_e32 v110, 0x3727c5ac, v110
	v_rsq_f32_e32 v110, v110
	v_pk_fma_f32 v[200:201], v[92:93], v[102:103], v[60:61] op_sel:[0,1,0] neg_lo:[1,0,0] neg_hi:[1,0,0]
	v_pk_fma_f32 v[60:61], v[198:199], v[102:103], v[62:63] op_sel:[0,1,0]
	v_pk_fma_f32 v[62:63], v[200:201], v[110:111], v[88:89] op_sel_hi:[1,0,1]
	v_pk_fma_f32 v[200:201], v[72:73], v[102:103], v[56:57] op_sel:[0,1,0] neg_lo:[1,0,0] neg_hi:[1,0,0]
	v_pk_fma_f32 v[56:57], v[196:197], v[102:103], v[58:59] op_sel:[0,1,0]
	v_pk_fma_f32 v[58:59], v[200:201], v[110:111], v[68:69] op_sel_hi:[1,0,1]
	v_pk_fma_f32 v[200:201], v[80:81], v[102:103], v[52:53] op_sel:[0,1,0] neg_lo:[1,0,0] neg_hi:[1,0,0]
	v_pk_fma_f32 v[52:53], v[194:195], v[102:103], v[54:55] op_sel:[0,1,0]
	v_pk_fma_f32 v[54:55], v[200:201], v[110:111], v[76:77] op_sel_hi:[1,0,1]
	v_pk_fma_f32 v[200:201], v[84:85], v[102:103], v[48:49] op_sel:[0,1,0] neg_lo:[1,0,0] neg_hi:[1,0,0]
	v_pk_fma_f32 v[48:49], v[192:193], v[102:103], v[50:51] op_sel:[0,1,0]
	v_cvt_f32_u32_e32 v102, v238
	v_cvt_f32_u32_e32 v103, v236
	v_cvt_f32_i32_e32 v98, v239
	v_pk_fma_f32 v[48:49], v[48:49], v[110:111], v[66:67] op_sel_hi:[1,0,1]
	v_pk_fma_f32 v[56:57], v[56:57], v[110:111], v[70:71] op_sel_hi:[1,0,1]
	v_pk_fma_f32 v[50:51], v[200:201], v[110:111], v[64:65] op_sel_hi:[1,0,1]
	v_pk_fma_f32 v[98:99], v[102:103], s[88:89], v[98:99] op_sel_hi:[1,0,1]
	v_pk_fma_f32 v[52:53], v[52:53], v[110:111], v[78:79] op_sel_hi:[1,0,1]
	v_pk_mul_f32 v[98:99], v[98:99], s[94:95] op_sel_hi:[1,0]
	v_pk_fma_f32 v[60:61], v[60:61], v[110:111], v[90:91] op_sel_hi:[1,0,1]
	v_fma_f32 v100, -v99, v99, v98
	v_add_f32_e32 v100, 0x3727c5ac, v100
	v_rsq_f32_e32 v100, v100
	v_pk_fma_f32 v[102:103], v[92:93], v[98:99], v[44:45] op_sel:[0,1,0] neg_lo:[1,0,0] neg_hi:[1,0,0]
	v_pk_fma_f32 v[44:45], v[198:199], v[98:99], v[46:47] op_sel:[0,1,0]
	v_max_f32_e32 v56, 0, v56
	v_pk_fma_f32 v[46:47], v[102:103], v[100:101], v[88:89] op_sel_hi:[1,0,1]
	v_pk_fma_f32 v[102:103], v[72:73], v[98:99], v[40:41] op_sel:[0,1,0] neg_lo:[1,0,0] neg_hi:[1,0,0]
	v_pk_fma_f32 v[40:41], v[196:197], v[98:99], v[42:43] op_sel:[0,1,0]
	v_pk_fma_f32 v[42:43], v[102:103], v[100:101], v[68:69] op_sel_hi:[1,0,1]
	v_pk_fma_f32 v[102:103], v[80:81], v[98:99], v[36:37] op_sel:[0,1,0] neg_lo:[1,0,0] neg_hi:[1,0,0]
	v_pk_fma_f32 v[36:37], v[194:195], v[98:99], v[38:39] op_sel:[0,1,0]
	v_pk_fma_f32 v[38:39], v[102:103], v[100:101], v[76:77] op_sel_hi:[1,0,1]
	v_pk_fma_f32 v[102:103], v[84:85], v[98:99], v[32:33] op_sel:[0,1,0] neg_lo:[1,0,0] neg_hi:[1,0,0]
	v_pk_fma_f32 v[32:33], v[192:193], v[98:99], v[34:35] op_sel:[0,1,0]
	v_cvt_f32_u32_e32 v98, v242
	v_cvt_f32_u32_e32 v99, v240
	v_cvt_f32_i32_e32 v96, v243
	v_pk_fma_f32 v[44:45], v[44:45], v[100:101], v[90:91] op_sel_hi:[1,0,1]
	v_pk_fma_f32 v[40:41], v[40:41], v[100:101], v[70:71] op_sel_hi:[1,0,1]
	v_pk_fma_f32 v[36:37], v[36:37], v[100:101], v[78:79] op_sel_hi:[1,0,1]
	v_pk_fma_f32 v[96:97], v[98:99], s[88:89], v[96:97] op_sel_hi:[1,0,1]
	v_pk_fma_f32 v[32:33], v[32:33], v[100:101], v[66:67] op_sel_hi:[1,0,1]
	v_pk_mul_f32 v[96:97], v[96:97], s[94:95] op_sel_hi:[1,0]
	v_pk_fma_f32 v[34:35], v[102:103], v[100:101], v[64:65] op_sel_hi:[1,0,1]
	v_fma_f32 v98, -v97, v97, v96
	v_add_f32_e32 v98, 0x3727c5ac, v98
	v_rsq_f32_e32 v98, v98
	v_pk_fma_f32 v[100:101], v[92:93], v[96:97], v[28:29] op_sel:[0,1,0] neg_lo:[1,0,0] neg_hi:[1,0,0]
	v_pk_fma_f32 v[28:29], v[198:199], v[96:97], v[30:31] op_sel:[0,1,0]
	v_max_f32_e32 v60, 0, v60
	v_pk_fma_f32 v[30:31], v[100:101], v[98:99], v[88:89] op_sel_hi:[1,0,1]
	v_pk_fma_f32 v[100:101], v[72:73], v[96:97], v[24:25] op_sel:[0,1,0] neg_lo:[1,0,0] neg_hi:[1,0,0]
	v_pk_fma_f32 v[24:25], v[196:197], v[96:97], v[26:27] op_sel:[0,1,0]
	v_pk_fma_f32 v[26:27], v[100:101], v[98:99], v[68:69] op_sel_hi:[1,0,1]
	v_pk_fma_f32 v[100:101], v[80:81], v[96:97], v[20:21] op_sel:[0,1,0] neg_lo:[1,0,0] neg_hi:[1,0,0]
	v_pk_fma_f32 v[20:21], v[194:195], v[96:97], v[22:23] op_sel:[0,1,0]
	v_pk_fma_f32 v[22:23], v[100:101], v[98:99], v[76:77] op_sel_hi:[1,0,1]
	v_pk_fma_f32 v[100:101], v[84:85], v[96:97], v[16:17] op_sel:[0,1,0] neg_lo:[1,0,0] neg_hi:[1,0,0]
	v_pk_fma_f32 v[16:17], v[192:193], v[96:97], v[18:19] op_sel:[0,1,0]
	v_pk_fma_f32 v[28:29], v[28:29], v[98:99], v[90:91] op_sel_hi:[1,0,1]
	v_pk_fma_f32 v[24:25], v[24:25], v[98:99], v[70:71] op_sel_hi:[1,0,1]
	v_pk_fma_f32 v[20:21], v[20:21], v[98:99], v[78:79] op_sel_hi:[1,0,1]
	v_pk_fma_f32 v[16:17], v[16:17], v[98:99], v[66:67] op_sel_hi:[1,0,1]
	v_pk_fma_f32 v[18:19], v[100:101], v[98:99], v[64:65] op_sel_hi:[1,0,1]
	v_cvt_f32_u32_e32 v96, v250
	v_cvt_f32_u32_e32 v97, v248
	v_cvt_f32_i32_e32 v98, v251
	v_cvt_f32_i32_e32 v99, v249
	v_max_f32_e32 v62, 0, v62
	v_max_f32_e32 v63, 0, v63
	v_mul_f32_e32 v60, v60, v60
	v_pk_fma_f32 v[96:97], v[96:97], s[88:89], v[98:99] op_sel_hi:[1,0,1]
	v_max_f32_e32 v57, 0, v57
	v_pk_mul_f32 v[96:97], v[96:97], s[94:95] op_sel_hi:[1,0]
	v_mul_f32_e32 v62, v62, v62
	v_fma_f32 v98, -v97, v97, v96
	v_add_f32_e32 v98, 0x3727c5ac, v98
	v_rsq_f32_e32 v98, v98
	v_pk_fma_f32 v[72:73], v[72:73], v[96:97], v[8:9] op_sel:[0,1,0] neg_lo:[1,0,0] neg_hi:[1,0,0]
	v_pk_fma_f32 v[8:9], v[196:197], v[96:97], v[10:11] op_sel:[0,1,0]
	v_mul_f32_e32 v63, v63, v63
	v_pk_fma_f32 v[10:11], v[72:73], v[98:99], v[68:69] op_sel_hi:[1,0,1]
	v_pk_fma_f32 v[68:69], v[80:81], v[96:97], v[4:5] op_sel:[0,1,0] neg_lo:[1,0,0] neg_hi:[1,0,0]
	v_pk_fma_f32 v[4:5], v[194:195], v[96:97], v[6:7] op_sel:[0,1,0]
	v_pk_fma_f32 v[6:7], v[68:69], v[98:99], v[76:77] op_sel_hi:[1,0,1]
	v_pk_fma_f32 v[68:69], v[84:85], v[96:97], v[0:1] op_sel:[0,1,0] neg_lo:[1,0,0] neg_hi:[1,0,0]
	v_pk_fma_f32 v[0:1], v[192:193], v[96:97], v[2:3] op_sel:[0,1,0]
	v_pk_fma_f32 v[8:9], v[8:9], v[98:99], v[70:71] op_sel_hi:[1,0,1]
	v_pk_fma_f32 v[0:1], v[0:1], v[98:99], v[66:67] op_sel_hi:[1,0,1]
	v_max_f32_e32 v67, 0, v190
	v_pk_fma_f32 v[2:3], v[68:69], v[98:99], v[64:65] op_sel_hi:[1,0,1]
	v_max_f32_e32 v66, 0, v188
	v_mul_f32_e32 v68, v67, v67
	v_max_f32_e32 v67, 0, v189
	v_max_f32_e32 v69, 0, v191
	v_max_f32_e32 v70, 0, v184
	v_max_f32_e32 v71, 0, v186
	v_lshlrev_b64 v[64:65], 14, v[180:181]
	v_mul_f32_e32 v66, v66, v66
	v_mul_f32_e32 v67, v67, v67
	v_mul_f32_e32 v69, v69, v69
	v_mul_f32_e32 v70, v70, v70
	v_mul_f32_e32 v71, v71, v71
	v_max_f32_e32 v72, 0, v185
	v_max_f32_e32 v73, 0, v187
	v_mul_f32_e32 v72, v72, v72
	v_mul_f32_e32 v73, v73, v73
	v_cvt_pk_bf16_f32 v66, v66, v67
	v_cvt_pk_bf16_f32 v67, v70, v72
	v_cvt_pk_bf16_f32 v68, v68, v69
	v_cvt_pk_bf16_f32 v69, v71, v73
	v_lshl_add_u64 v[64:65], s[36:37], 0, v[64:65]
	v_lshlrev_b64 v[70:71], 1, v[182:183]
	v_lshl_add_u64 v[64:65], v[64:65], 0, v[70:71]
	global_store_dwordx4 v[64:65], v[66:69], off nt
	v_max_f32_e32 v72, 0, v152
	v_max_f32_e32 v73, 0, v154
	v_max_f32_e32 v66, 0, v156
	v_max_f32_e32 v67, 0, v158
	v_mul_f32_e32 v66, v66, v66
	v_mul_f32_e32 v68, v67, v67
	v_max_f32_e32 v67, 0, v157
	v_max_f32_e32 v69, 0, v159
	v_mul_f32_e32 v67, v67, v67
	v_mul_f32_e32 v69, v69, v69
	v_max_f32_e32 v76, 0, v153
	v_max_f32_e32 v77, 0, v155
	v_cvt_pk_bf16_f32 v66, v66, v67
	v_mul_f32_e32 v72, v72, v72
	v_mul_f32_e32 v73, v73, v73
	v_mul_f32_e32 v76, v76, v76
	v_mul_f32_e32 v77, v77, v77
	v_cvt_pk_bf16_f32 v67, v72, v76
	v_cvt_pk_bf16_f32 v68, v68, v69
	v_cvt_pk_bf16_f32 v69, v73, v77
	global_store_dwordx4 v[64:65], v[66:69], off offset:256 nt
	v_pk_fma_f32 v[4:5], v[4:5], v[98:99], v[78:79] op_sel_hi:[1,0,1]
	v_max_f32_e32 v76, 0, v144
	v_or_b32_e32 v66, 16, v180
	v_ashrrev_i32_e32 v67, 31, v66
	v_lshlrev_b64 v[72:73], 14, v[66:67]
	v_max_f32_e32 v67, 0, v150
	v_max_f32_e32 v66, 0, v148
	v_mul_f32_e32 v68, v67, v67
	v_max_f32_e32 v67, 0, v149
	v_mul_f32_e32 v66, v66, v66
	v_max_f32_e32 v69, 0, v151
	v_mul_f32_e32 v67, v67, v67
	v_max_f32_e32 v78, 0, v145
	v_lshl_add_u64 v[72:73], s[36:37], 0, v[72:73]
	v_mul_f32_e32 v69, v69, v69
	v_max_f32_e32 v77, 0, v146
	v_mul_f32_e32 v76, v76, v76
	v_max_f32_e32 v79, 0, v147
	v_mul_f32_e32 v78, v78, v78
	v_cvt_pk_bf16_f32 v66, v66, v67
	v_cvt_pk_bf16_f32 v67, v76, v78
	v_lshl_add_u64 v[72:73], v[72:73], 0, v[70:71]
	v_mul_f32_e32 v77, v77, v77
	v_mul_f32_e32 v79, v79, v79
	v_cvt_pk_bf16_f32 v68, v68, v69
	v_cvt_pk_bf16_f32 v69, v77, v79
	global_store_dwordx4 v[72:73], v[66:69], off nt
	v_max_f32_e32 v76, 0, v136
	v_max_f32_e32 v77, 0, v138
	v_max_f32_e32 v66, 0, v140
	v_max_f32_e32 v67, 0, v142
	v_mul_f32_e32 v66, v66, v66
	v_mul_f32_e32 v68, v67, v67
	v_max_f32_e32 v67, 0, v141
	v_max_f32_e32 v69, 0, v143
	v_mul_f32_e32 v67, v67, v67
	v_mul_f32_e32 v69, v69, v69
	v_max_f32_e32 v78, 0, v137
	v_max_f32_e32 v79, 0, v139
	v_cvt_pk_bf16_f32 v66, v66, v67
	v_mul_f32_e32 v76, v76, v76
	v_mul_f32_e32 v77, v77, v77
	v_mul_f32_e32 v78, v78, v78
	v_mul_f32_e32 v79, v79, v79
	v_cvt_pk_bf16_f32 v67, v76, v78
	v_cvt_pk_bf16_f32 v68, v68, v69
	v_cvt_pk_bf16_f32 v69, v77, v79
	global_store_dwordx4 v[72:73], v[66:69], off offset:256 nt
	v_max_f32_e32 v76, 0, v128
	v_max_f32_e32 v78, 0, v129
	v_or_b32_e32 v66, 32, v180
	v_ashrrev_i32_e32 v67, 31, v66
	v_lshlrev_b64 v[72:73], 14, v[66:67]
	v_max_f32_e32 v67, 0, v132
	v_max_f32_e32 v66, 0, v130
	v_mul_f32_e32 v68, v67, v67
	v_max_f32_e32 v67, 0, v131
	v_mul_f32_e32 v66, v66, v66
	v_max_f32_e32 v69, 0, v133
	v_mul_f32_e32 v67, v67, v67
	v_lshl_add_u64 v[72:73], s[36:37], 0, v[72:73]
	v_mul_f32_e32 v69, v69, v69
	v_max_f32_e32 v77, 0, v126
	v_mul_f32_e32 v76, v76, v76
	v_max_f32_e32 v79, 0, v127
	v_mul_f32_e32 v78, v78, v78
	v_cvt_pk_bf16_f32 v66, v66, v67
	v_cvt_pk_bf16_f32 v67, v76, v78
	v_lshl_add_u64 v[72:73], v[72:73], 0, v[70:71]
	v_mul_f32_e32 v77, v77, v77
	v_mul_f32_e32 v79, v79, v79
	v_cvt_pk_bf16_f32 v68, v68, v69
	v_cvt_pk_bf16_f32 v69, v77, v79
	global_store_dwordx4 v[72:73], v[66:69], off nt
	v_max_f32_e32 v76, 0, v114
	v_max_f32_e32 v77, 0, v120
	v_max_f32_e32 v66, 0, v122
	v_max_f32_e32 v67, 0, v124
	v_mul_f32_e32 v66, v66, v66
	v_mul_f32_e32 v68, v67, v67
	v_max_f32_e32 v67, 0, v123
	v_max_f32_e32 v69, 0, v125
	v_mul_f32_e32 v67, v67, v67
	v_mul_f32_e32 v69, v69, v69
	v_max_f32_e32 v78, 0, v115
	v_max_f32_e32 v79, 0, v121
	v_cvt_pk_bf16_f32 v66, v66, v67
	v_mul_f32_e32 v76, v76, v76
	v_mul_f32_e32 v77, v77, v77
	v_mul_f32_e32 v78, v78, v78
	v_mul_f32_e32 v79, v79, v79
	v_cvt_pk_bf16_f32 v67, v76, v78
	v_cvt_pk_bf16_f32 v68, v68, v69
	v_cvt_pk_bf16_f32 v69, v77, v79
	global_store_dwordx4 v[72:73], v[66:69], off offset:256 nt
	v_max_f32_e32 v76, 0, v104
	v_max_f32_e32 v78, 0, v105
	v_or_b32_e32 v66, 48, v180
	v_ashrrev_i32_e32 v67, 31, v66
	v_lshlrev_b64 v[72:73], 14, v[66:67]
	v_max_f32_e32 v67, 0, v108
	v_max_f32_e32 v66, 0, v112
	v_mul_f32_e32 v68, v67, v67
	v_max_f32_e32 v67, 0, v113
	v_mul_f32_e32 v66, v66, v66
	v_max_f32_e32 v69, 0, v109
	v_mul_f32_e32 v67, v67, v67
	v_lshl_add_u64 v[72:73], s[36:37], 0, v[72:73]
	v_mul_f32_e32 v69, v69, v69
	v_max_f32_e32 v77, 0, v106
	v_mul_f32_e32 v76, v76, v76
	v_max_f32_e32 v79, 0, v107
	v_mul_f32_e32 v78, v78, v78
	v_cvt_pk_bf16_f32 v66, v66, v67
	v_cvt_pk_bf16_f32 v67, v76, v78
	v_lshl_add_u64 v[70:71], v[72:73], 0, v[70:71]
	v_mul_f32_e32 v77, v77, v77
	v_mul_f32_e32 v79, v79, v79
	v_cvt_pk_bf16_f32 v68, v68, v69
	v_cvt_pk_bf16_f32 v69, v77, v79
	global_store_dwordx4 v[70:71], v[66:69], off nt
	v_max_f32_e32 v72, 0, v74
	v_max_f32_e32 v73, 0, v82
	v_max_f32_e32 v66, 0, v86
	v_max_f32_e32 v67, 0, v94
	v_mul_f32_e32 v66, v66, v66
	v_mul_f32_e32 v68, v67, v67
	v_max_f32_e32 v67, 0, v87
	v_max_f32_e32 v69, 0, v95
	v_mul_f32_e32 v67, v67, v67
	v_mul_f32_e32 v69, v69, v69
	v_max_f32_e32 v74, 0, v75
	v_max_f32_e32 v75, 0, v83
	v_cvt_pk_bf16_f32 v66, v66, v67
	v_mul_f32_e32 v72, v72, v72
	v_mul_f32_e32 v73, v73, v73
	v_mul_f32_e32 v74, v74, v74
	v_mul_f32_e32 v75, v75, v75
	v_cvt_pk_bf16_f32 v67, v72, v74
	v_cvt_pk_bf16_f32 v68, v68, v69
	v_cvt_pk_bf16_f32 v69, v73, v75
	global_store_dwordx4 v[70:71], v[66:69], off offset:256 nt
	v_max_f32_e32 v58, 0, v58
	v_max_f32_e32 v59, 0, v59
	v_mul_f32_e32 v66, v56, v56
	v_max_f32_e32 v56, 0, v61
	v_mul_f32_e32 v61, v56, v56
	v_mul_f32_e32 v67, v57, v57
	v_cvt_pk_bf16_f32 v56, v62, v63
	v_cvt_pk_bf16_f32 v57, v60, v61
	v_lshl_add_u64 v[60:61], v[64:65], 0, s[0:1]
	s_mov_b32 s0, 0x200000
	v_add_co_u32_e32 v62, vcc, s0, v64
	v_mul_f32_e32 v58, v58, v58
	v_mul_f32_e32 v59, v59, v59
	v_addc_co_u32_e32 v63, vcc, 0, v65, vcc
	v_max_f32_e32 v48, 0, v48
	v_cvt_pk_bf16_f32 v58, v58, v59
	v_cvt_pk_bf16_f32 v59, v66, v67
	global_store_dwordx4 v[62:63], v[56:59], off nt
	v_max_f32_e32 v54, 0, v54
	v_max_f32_e32 v50, 0, v50
	v_max_f32_e32 v55, 0, v55
	v_max_f32_e32 v51, 0, v51
	v_mul_f32_e32 v56, v48, v48
	v_max_f32_e32 v48, 0, v53
	v_mul_f32_e32 v54, v54, v54
	v_mul_f32_e32 v50, v50, v50
	v_mul_f32_e32 v55, v55, v55
	v_mul_f32_e32 v51, v51, v51
	v_max_f32_e32 v52, 0, v52
	v_max_f32_e32 v49, 0, v49
	v_mul_f32_e32 v53, v48, v48
	v_cvt_pk_bf16_f32 v48, v54, v55
	v_max_f32_e32 v40, 0, v40
	v_mul_f32_e32 v52, v52, v52
	v_mul_f32_e32 v57, v49, v49
	v_cvt_pk_bf16_f32 v49, v52, v53
	v_cvt_pk_bf16_f32 v50, v50, v51
	v_cvt_pk_bf16_f32 v51, v56, v57
	global_store_dwordx4 v[60:61], v[48:51], off offset:256 nt
	v_max_f32_e32 v44, 0, v44
	v_max_f32_e32 v46, 0, v46
	v_mul_f32_e32 v48, v40, v40
	v_max_f32_e32 v40, 0, v45
	v_max_f32_e32 v47, 0, v47
	v_mul_f32_e32 v44, v44, v44
	v_max_f32_e32 v41, 0, v41
	v_mul_f32_e32 v45, v40, v40
	s_mov_b64 s[0:1], 0x240000
	v_mul_f32_e32 v46, v46, v46
	v_mul_f32_e32 v47, v47, v47
	v_mul_f32_e32 v49, v41, v41
	v_cvt_pk_bf16_f32 v40, v46, v47
	v_cvt_pk_bf16_f32 v41, v44, v45
	v_lshl_add_u64 v[44:45], v[64:65], 0, s[0:1]
	s_mov_b32 s0, 0x240000
	v_max_f32_e32 v42, 0, v42
	v_max_f32_e32 v43, 0, v43
	v_add_co_u32_e32 v46, vcc, s0, v64
	v_mul_f32_e32 v42, v42, v42
	v_mul_f32_e32 v43, v43, v43
	v_addc_co_u32_e32 v47, vcc, 0, v65, vcc
	v_max_f32_e32 v32, 0, v32
	v_cvt_pk_bf16_f32 v42, v42, v43
	v_cvt_pk_bf16_f32 v43, v48, v49
	global_store_dwordx4 v[46:47], v[40:43], off nt
	v_max_f32_e32 v38, 0, v38
	v_max_f32_e32 v34, 0, v34
	v_max_f32_e32 v39, 0, v39
	v_max_f32_e32 v35, 0, v35
	v_mul_f32_e32 v40, v32, v32
	v_max_f32_e32 v32, 0, v37
	v_mul_f32_e32 v38, v38, v38
	v_mul_f32_e32 v34, v34, v34
	v_mul_f32_e32 v39, v39, v39
	v_mul_f32_e32 v35, v35, v35
	v_max_f32_e32 v36, 0, v36
	v_max_f32_e32 v33, 0, v33
	v_mul_f32_e32 v37, v32, v32
	v_cvt_pk_bf16_f32 v32, v38, v39
	v_max_f32_e32 v24, 0, v24
	v_mul_f32_e32 v36, v36, v36
	v_mul_f32_e32 v41, v33, v33
	v_cvt_pk_bf16_f32 v33, v36, v37
	v_cvt_pk_bf16_f32 v34, v34, v35
	v_cvt_pk_bf16_f32 v35, v40, v41
	global_store_dwordx4 v[44:45], v[32:35], off offset:256 nt
	v_max_f32_e32 v28, 0, v28
	v_max_f32_e32 v30, 0, v30
	v_mul_f32_e32 v32, v24, v24
	v_max_f32_e32 v24, 0, v29
	v_max_f32_e32 v31, 0, v31
	v_mul_f32_e32 v28, v28, v28
	v_max_f32_e32 v25, 0, v25
	v_mul_f32_e32 v29, v24, v24
	s_mov_b64 s[0:1], 0x280000
	v_mul_f32_e32 v30, v30, v30
	v_mul_f32_e32 v31, v31, v31
	v_mul_f32_e32 v33, v25, v25
	v_cvt_pk_bf16_f32 v24, v30, v31
	v_cvt_pk_bf16_f32 v25, v28, v29
	v_lshl_add_u64 v[28:29], v[64:65], 0, s[0:1]
	s_mov_b32 s0, 0x280000
	v_max_f32_e32 v26, 0, v26
	v_max_f32_e32 v27, 0, v27
	v_add_co_u32_e32 v30, vcc, s0, v64
	v_mul_f32_e32 v26, v26, v26
	v_mul_f32_e32 v27, v27, v27
	v_addc_co_u32_e32 v31, vcc, 0, v65, vcc
	v_max_f32_e32 v16, 0, v16
	v_pk_fma_f32 v[92:93], v[92:93], v[96:97], v[12:13] op_sel:[0,1,0] neg_lo:[1,0,0] neg_hi:[1,0,0]
	v_pk_fma_f32 v[12:13], v[198:199], v[96:97], v[14:15] op_sel:[0,1,0]
	v_cvt_pk_bf16_f32 v26, v26, v27
	v_cvt_pk_bf16_f32 v27, v32, v33
	global_store_dwordx4 v[30:31], v[24:27], off nt
	v_max_f32_e32 v22, 0, v22
	v_max_f32_e32 v18, 0, v18
	v_max_f32_e32 v23, 0, v23
	v_max_f32_e32 v19, 0, v19
	v_mul_f32_e32 v24, v16, v16
	v_max_f32_e32 v16, 0, v21
	v_pk_fma_f32 v[12:13], v[12:13], v[98:99], v[90:91] op_sel_hi:[1,0,1]
	v_mul_f32_e32 v22, v22, v22
	v_mul_f32_e32 v18, v18, v18
	v_mul_f32_e32 v23, v23, v23
	v_mul_f32_e32 v19, v19, v19
	v_max_f32_e32 v20, 0, v20
	v_max_f32_e32 v17, 0, v17
	v_mul_f32_e32 v21, v16, v16
	v_cvt_pk_bf16_f32 v16, v22, v23
	v_max_f32_e32 v8, 0, v8
	v_pk_fma_f32 v[14:15], v[92:93], v[98:99], v[88:89] op_sel_hi:[1,0,1]
	v_mul_f32_e32 v20, v20, v20
	v_mul_f32_e32 v25, v17, v17
	v_cvt_pk_bf16_f32 v17, v20, v21
	v_cvt_pk_bf16_f32 v18, v18, v19
	v_cvt_pk_bf16_f32 v19, v24, v25
	global_store_dwordx4 v[28:29], v[16:19], off offset:256 nt
	v_max_f32_e32 v12, 0, v12
	v_max_f32_e32 v14, 0, v14
	v_mul_f32_e32 v16, v8, v8
	v_max_f32_e32 v8, 0, v13
	v_max_f32_e32 v15, 0, v15
	v_mul_f32_e32 v12, v12, v12
	v_max_f32_e32 v9, 0, v9
	v_mul_f32_e32 v13, v8, v8
	s_mov_b64 s[0:1], 0x2c0000
	v_mul_f32_e32 v14, v14, v14
	v_mul_f32_e32 v15, v15, v15
	v_mul_f32_e32 v17, v9, v9
	v_cvt_pk_bf16_f32 v8, v14, v15
	v_cvt_pk_bf16_f32 v9, v12, v13
	v_lshl_add_u64 v[12:13], v[64:65], 0, s[0:1]
	s_mov_b32 s0, 0x2c0000
	v_max_f32_e32 v10, 0, v10
	v_max_f32_e32 v11, 0, v11
	v_add_co_u32_e32 v14, vcc, s0, v64
	v_mul_f32_e32 v10, v10, v10
	v_mul_f32_e32 v11, v11, v11
	v_addc_co_u32_e32 v15, vcc, 0, v65, vcc
	v_max_f32_e32 v2, 0, v2
	v_max_f32_e32 v3, 0, v3
	v_max_f32_e32 v0, 0, v0
	v_cvt_pk_bf16_f32 v10, v10, v11
	v_cvt_pk_bf16_f32 v11, v16, v17
	global_store_dwordx4 v[14:15], v[8:11], off nt
	v_max_f32_e32 v6, 0, v6
	v_mul_f32_e32 v2, v2, v2
	v_max_f32_e32 v7, 0, v7
	v_mul_f32_e32 v3, v3, v3
	v_max_f32_e32 v4, 0, v4
	v_mul_f32_e32 v8, v0, v0
	v_max_f32_e32 v0, 0, v5
	v_max_f32_e32 v1, 0, v1
	s_and_b64 vcc, exec, s[6:7]
	s_mov_b64 s[0:1], s[76:77]
	v_mul_f32_e32 v6, v6, v6
	v_mul_f32_e32 v7, v7, v7
	v_mul_f32_e32 v4, v4, v4
	v_mul_f32_e32 v5, v0, v0
	v_mul_f32_e32 v9, v1, v1
	v_cvt_pk_bf16_f32 v0, v6, v7
	v_cvt_pk_bf16_f32 v1, v4, v5
	v_cvt_pk_bf16_f32 v2, v2, v3
	v_cvt_pk_bf16_f32 v3, v8, v9
	global_store_dwordx4 v[12:13], v[0:3], off offset:256 nt
	s_cbranch_vccz .LBB0_1049
	s_waitcnt vmcnt(0)
	v_readlane_b32 s38, v255, 9
	s_cmpk_gt_u32 s18, 0xff
	v_readlane_b32 s39, v255, 10
	s_cbranch_scc1 .LBB0_1060
	s_barrier
